# up-GEMM epilogue: rstd reads and conv-weight loads issued at loop exit, before the aligned-epilogue barrier
# speedup vs baseline: 1.0019x; 1.0019x over previous
; #define PG8_STAGE(bufoff, gbase, voff) do { _Pragma("unroll") for (int _i = 0; _i < 2; ++_i) \
;         __builtin_amdgcn_global_load_lds((const unsigned*)((const char*)(gbase) + (voff)[_i]), (LAS unsigned*)(lds + (bufoff) + ldsw + _i * 8192), 16, 0, 0); } while (0)
; #define PG8_LDA(dst, b, h) do { _Pragma("unroll") for (int m = 0; m < 4; ++m) _Pragma("unroll") for (int k = 0; k < 2; ++k) dst[m][k] = *(const LAS bf16x8*)(lds + PG8_SA(b, h) + aoff + m * 2048 + k * 1024); } while (0)
; #define PG8_LDB(dst, b, h) do { _Pragma("unroll") for (int n = 0; n < 2; ++n) _Pragma("unroll") for (int k = 0; k < 2; ++k) dst[n][k] = *(const LAS bf16x8*)(lds + PG8_SB(b, h) + boff + n * 2048 + k * 1024); } while (0)
; #define PG8_MMA(ai, bj, At, Bt) do { __builtin_amdgcn_s_setprio(1); _Pragma("unroll") for (int m = 0; m < 4; ++m) _Pragma("unroll") for (int n = 0; n < 2; ++n) _Pragma("unroll") for (int k = 0; k < 2; ++k) \
;         acc[ai][bj][m][n] = __builtin_amdgcn_mfma_f32_16x16x32_bf16(Bt[n][k], At[m][k], acc[ai][bj][m][n], 0, 0, 0); __builtin_amdgcn_s_setprio(0); } while (0)
; #define PG8_WAIT_V(n) asm volatile("s_waitcnt vmcnt(" #n ")" ::: "memory")
; #define PG8_WAIT_L(n) asm volatile("s_waitcnt lgkmcnt(" #n ")" ::: "memory")
; #define PG8_BAR __builtin_amdgcn_s_barrier()
; #define PG8_SCHED __builtin_amdgcn_sched_barrier(0)
; template <class Epi, bool KREV = false>
; __device__ __forceinline__ void gemm_phase(LAS unsigned char* lds, const Gemm g, const StaticOrder& S, const Epi& E, int wave_s) {
;     ...
;             PG8_LDB(B0, 0, 0); PG8_LDB(B1, 0, 1); PG8_SCHED; PG8_LDA(At, 0, 0); PG8_STAGE(PG8_SA(1, 1), a1 + hstep, voffA);
;             PG8_WAIT_V(8); PG8_WAIT_L(0); PG8_BAR; PG8_MMA(0, 0, At, B0); PG8_MMA(0, 1, At, B1); PG8_BAR; PG8_SCHED;
;             PG8_LDA(At, 0, 1); PG8_STAGE(PG8_SB(0, 0), b2, voffB); PG8_STAGE(PG8_SB(0, 1), b2 + bh, voffB); PG8_STAGE(PG8_SA(0, 0), a2, voffA);
.Lsb2:
.LBB0_836:
	v_add_u32_e32 v154, 0x10000, v135
	v_add_u32_e32 v170, 0x14000, v135
	ds_read_b128 v[142:145], v154
	ds_read_b128 v[146:149], v154 offset:1024
	ds_read_b128 v[150:153], v154 offset:2048
	ds_read_b128 v[154:157], v154 offset:3072
	ds_read_b128 v[158:161], v170
	ds_read_b128 v[162:165], v170 offset:1024
	ds_read_b128 v[166:169], v170 offset:2048
	ds_read_b128 v[170:173], v170 offset:3072
	ds_read_b128 v[178:181], v194
	ds_read_b128 v[182:185], v194 offset:1024
	ds_read_b128 v[186:189], v194 offset:2048
	ds_read_b128 v[196:199], v194 offset:3072
	ds_read_b128 v[200:203], v194 offset:4096
	ds_read_b128 v[204:207], v194 offset:5120
	ds_read_b128 v[218:221], v194 offset:6144
	ds_read_b128 v[222:225], v194 offset:7168
	s_add_u32 s56, s54, 0xfff80080
	s_addc_u32 s57, s55, -1
	s_add_i32 s84, 0, 0x10000
	s_cmp_eq_u32 s83, 28
	s_cselect_b32 s59, s73, s57
	s_cselect_b32 s58, s74, s56
	s_cselect_b32 s57, s75, s82
	s_cselect_b32 s56, s77, s80
	s_add_i32 s86, 0, 0x14000
	s_add_i32 m0, s19, 0xc000
	s_nop 0
	global_load_lds_dwordx4 v138, s[54:55]
	s_add_i32 m0, s19, 0xe000
	s_nop 0
	global_load_lds_dwordx4 v140, s[54:55]
	s_waitcnt vmcnt(8)
	s_waitcnt lgkmcnt(0)
	s_barrier
	s_setprio 1
	s_waitcnt lgkmcnt(0)
	v_mfma_f32_16x16x32_bf16 v[124:127], v[142:145], v[178:181], v[124:127]
	v_mfma_f32_16x16x32_bf16 v[120:123], v[150:153], v[178:181], v[120:123]
	v_mfma_f32_16x16x32_bf16 v[68:71], v[142:145], v[186:189], v[68:71]
	v_mfma_f32_16x16x32_bf16 v[64:67], v[150:153], v[186:189], v[64:67]
	v_mfma_f32_16x16x32_bf16 v[60:63], v[142:145], v[200:203], v[60:63]
	v_mfma_f32_16x16x32_bf16 v[20:23], v[150:153], v[200:203], v[20:23]
	v_mfma_f32_16x16x32_bf16 v[108:111], v[142:145], v[218:221], v[108:111]
	v_mfma_f32_16x16x32_bf16 v[104:107], v[150:153], v[218:221], v[104:107]
	v_mfma_f32_16x16x32_bf16 v[124:127], v[146:149], v[182:185], v[124:127]
	v_mfma_f32_16x16x32_bf16 v[120:123], v[154:157], v[182:185], v[120:123]
	v_mfma_f32_16x16x32_bf16 v[68:71], v[146:149], v[196:199], v[68:71]
	v_mfma_f32_16x16x32_bf16 v[64:67], v[154:157], v[196:199], v[64:67]
	v_mfma_f32_16x16x32_bf16 v[60:63], v[146:149], v[204:207], v[60:63]
	v_mfma_f32_16x16x32_bf16 v[20:23], v[154:157], v[204:207], v[20:23]
	v_mfma_f32_16x16x32_bf16 v[108:111], v[146:149], v[222:225], v[108:111]
	v_mfma_f32_16x16x32_bf16 v[104:107], v[154:157], v[222:225], v[104:107]
	s_setprio 0
	s_setprio 1
	v_mfma_f32_16x16x32_bf16 v[116:119], v[158:161], v[178:181], v[116:119]
	v_mfma_f32_16x16x32_bf16 v[112:115], v[166:169], v[178:181], v[112:115]
	v_mfma_f32_16x16x32_bf16 v[52:55], v[158:161], v[186:189], v[52:55]
	v_mfma_f32_16x16x32_bf16 v[48:51], v[166:169], v[186:189], v[48:51]
	v_mfma_f32_16x16x32_bf16 v[44:47], v[158:161], v[200:203], v[44:47]
	v_mfma_f32_16x16x32_bf16 v[16:19], v[166:169], v[200:203], v[16:19]
	v_mfma_f32_16x16x32_bf16 v[100:103], v[158:161], v[218:221], v[100:103]
	v_mfma_f32_16x16x32_bf16 v[96:99], v[166:169], v[218:221], v[96:99]
	v_mfma_f32_16x16x32_bf16 v[116:119], v[162:165], v[182:185], v[116:119]
	v_mfma_f32_16x16x32_bf16 v[112:115], v[170:173], v[182:185], v[112:115]
	v_mfma_f32_16x16x32_bf16 v[52:55], v[162:165], v[196:199], v[52:55]
	v_mfma_f32_16x16x32_bf16 v[48:51], v[170:173], v[196:199], v[48:51]
	v_mfma_f32_16x16x32_bf16 v[44:47], v[162:165], v[204:207], v[44:47]
	v_mfma_f32_16x16x32_bf16 v[16:19], v[170:173], v[204:207], v[16:19]
	v_mfma_f32_16x16x32_bf16 v[100:103], v[162:165], v[222:225], v[100:103]
	s_barrier
	v_mfma_f32_16x16x32_bf16 v[96:99], v[170:173], v[222:225], v[96:99]
	s_setprio 0
	s_add_u32 s98, s56, s2
	s_addc_u32 s99, s57, s3
	s_add_u32 s100, s58, s2
	s_addc_u32 s101, s59, s3
	s_add_i32 s84, s84, s66
	s_mov_b32 m0, s84
	ds_read_b128 v[178:181], v194 offset:16384
	ds_read_b128 v[182:185], v194 offset:17408
	ds_read_b128 v[186:189], v194 offset:18432
	ds_read_b128 v[196:199], v194 offset:19456
	ds_read_b128 v[200:203], v194 offset:20480
	ds_read_b128 v[204:207], v194 offset:21504
	ds_read_b128 v[218:221], v194 offset:22528
	ds_read_b128 v[222:225], v194 offset:23552
	global_load_lds_dwordx4 v176, s[56:57]
	s_add_i32 m0, s84, 0x2000
	s_add_u32 s84, s56, 0x1600000
	s_addc_u32 s85, s57, 0
	s_add_i32 s86, s86, s66
	global_load_lds_dwordx4 v132, s[56:57]
	s_mov_b32 m0, s86
	s_nop 0
	global_load_lds_dwordx4 v176, s[84:85]
	s_add_i32 m0, s86, 0x2000
	s_nop 0
	global_load_lds_dwordx4 v132, s[84:85]
	s_mov_b32 m0, s19
	s_nop 0
	global_load_lds_dwordx4 v128, s[58:59]
	s_mov_b32 m0, s21
	s_nop 0
	global_load_lds_dwordx4 v130, s[58:59]
	s_waitcnt vmcnt(8)
	s_waitcnt lgkmcnt(0)
	s_barrier
; #define PG8_STAGE(bufoff, gbase, voff) do { _Pragma("unroll") for (int _i = 0; _i < 2; ++_i) \
;         __builtin_amdgcn_global_load_lds((const unsigned*)((const char*)(gbase) + (voff)[_i]), (LAS unsigned*)(lds + (bufoff) + ldsw + _i * 8192), 16, 0, 0); } while (0)
; #define PG8_LDA(dst, b, h) do { _Pragma("unroll") for (int m = 0; m < 4; ++m) _Pragma("unroll") for (int k = 0; k < 2; ++k) dst[m][k] = *(const LAS bf16x8*)(lds + PG8_SA(b, h) + aoff + m * 2048 + k * 1024); } while (0)
; #define PG8_LDB(dst, b, h) do { _Pragma("unroll") for (int n = 0; n < 2; ++n) _Pragma("unroll") for (int k = 0; k < 2; ++k) dst[n][k] = *(const LAS bf16x8*)(lds + PG8_SB(b, h) + boff + n * 2048 + k * 1024); } while (0)
; #define PG8_MMA(ai, bj, At, Bt) do { __builtin_amdgcn_s_setprio(1); _Pragma("unroll") for (int m = 0; m < 4; ++m) _Pragma("unroll") for (int n = 0; n < 2; ++n) _Pragma("unroll") for (int k = 0; k < 2; ++k) \
;         acc[ai][bj][m][n] = __builtin_amdgcn_mfma_f32_16x16x32_bf16(Bt[n][k], At[m][k], acc[ai][bj][m][n], 0, 0, 0); __builtin_amdgcn_s_setprio(0); } while (0)
; #define PG8_WAIT_V(n) asm volatile("s_waitcnt vmcnt(" #n ")" ::: "memory")
; #define PG8_WAIT_L(n) asm volatile("s_waitcnt lgkmcnt(" #n ")" ::: "memory")
; #define PG8_BAR __builtin_amdgcn_s_barrier()
; #define PG8_SCHED __builtin_amdgcn_sched_barrier(0)
; template <class Epi, bool KREV = false>
; __device__ __forceinline__ void gemm_phase(LAS unsigned char* lds, const Gemm g, const StaticOrder& S, const Epi& E, int wave_s) {
;     ...
;             PG8_LDB(B0, 0, 0); PG8_LDB(B1, 0, 1); PG8_SCHED; PG8_LDA(At, 0, 0); PG8_STAGE(PG8_SA(1, 1), a1 + hstep, voffA);
;             PG8_WAIT_V(8); PG8_WAIT_L(0); PG8_BAR; PG8_MMA(0, 0, At, B0); PG8_MMA(0, 1, At, B1); PG8_BAR; PG8_SCHED;
;             PG8_LDA(At, 0, 1); PG8_STAGE(PG8_SB(0, 0), b2, voffB); PG8_STAGE(PG8_SB(0, 1), b2 + bh, voffB); PG8_STAGE(PG8_SA(0, 0), a2, voffA);
;             PG8_WAIT_V(8); PG8_WAIT_L(0); PG8_BAR; PG8_MMA(1, 0, At, B0); PG8_MMA(1, 1, At, B1); PG8_BAR; PG8_SCHED;
;             PG8_LDB(B0, 1, 0); PG8_LDB(B1, 1, 1); PG8_SCHED; PG8_LDA(At, 1, 0); PG8_STAGE(PG8_SA(0, 1), a2 + hstep, voffA);
;             PG8_WAIT_V(8); PG8_WAIT_L(0); PG8_BAR; PG8_MMA(0, 0, At, B0); PG8_MMA(0, 1, At, B1); PG8_BAR; PG8_SCHED;
	s_setprio 1
	s_waitcnt lgkmcnt(0)
	v_mfma_f32_16x16x32_bf16 v[92:95], v[142:145], v[178:181], v[92:95]
	v_mfma_f32_16x16x32_bf16 v[88:91], v[150:153], v[178:181], v[88:91]
	v_mfma_f32_16x16x32_bf16 v[36:39], v[142:145], v[186:189], v[36:39]
	v_mfma_f32_16x16x32_bf16 v[12:15], v[150:153], v[186:189], v[12:15]
	v_mfma_f32_16x16x32_bf16 v[32:35], v[142:145], v[200:203], v[32:35]
	v_mfma_f32_16x16x32_bf16 v[4:7], v[150:153], v[200:203], v[4:7]
	v_mfma_f32_16x16x32_bf16 v[76:79], v[142:145], v[218:221], v[76:79]
	v_mfma_f32_16x16x32_bf16 v[56:59], v[150:153], v[218:221], v[56:59]
	v_mfma_f32_16x16x32_bf16 v[92:95], v[146:149], v[182:185], v[92:95]
	v_mfma_f32_16x16x32_bf16 v[88:91], v[154:157], v[182:185], v[88:91]
	v_mfma_f32_16x16x32_bf16 v[36:39], v[146:149], v[196:199], v[36:39]
	v_mfma_f32_16x16x32_bf16 v[12:15], v[154:157], v[196:199], v[12:15]
	v_mfma_f32_16x16x32_bf16 v[32:35], v[146:149], v[204:207], v[32:35]
	v_mfma_f32_16x16x32_bf16 v[4:7], v[154:157], v[204:207], v[4:7]
	v_mfma_f32_16x16x32_bf16 v[76:79], v[146:149], v[222:225], v[76:79]
	v_mfma_f32_16x16x32_bf16 v[56:59], v[154:157], v[222:225], v[56:59]
	s_setprio 0
	s_setprio 1
	v_mfma_f32_16x16x32_bf16 v[84:87], v[158:161], v[178:181], v[84:87]
	v_mfma_f32_16x16x32_bf16 v[80:83], v[166:169], v[178:181], v[80:83]
	v_mfma_f32_16x16x32_bf16 v[28:31], v[158:161], v[186:189], v[28:31]
	v_mfma_f32_16x16x32_bf16 v[8:11], v[166:169], v[186:189], v[8:11]
	v_mfma_f32_16x16x32_bf16 v[24:27], v[158:161], v[200:203], v[24:27]
	v_mfma_f32_16x16x32_bf16 v[0:3], v[166:169], v[200:203], v[0:3]
	v_mfma_f32_16x16x32_bf16 v[72:75], v[158:161], v[218:221], v[72:75]
	v_mfma_f32_16x16x32_bf16 v[40:43], v[166:169], v[218:221], v[40:43]
	v_mfma_f32_16x16x32_bf16 v[84:87], v[162:165], v[182:185], v[84:87]
	v_mfma_f32_16x16x32_bf16 v[80:83], v[170:173], v[182:185], v[80:83]
	v_mfma_f32_16x16x32_bf16 v[28:31], v[162:165], v[196:199], v[28:31]
	v_mfma_f32_16x16x32_bf16 v[8:11], v[170:173], v[196:199], v[8:11]
	v_mfma_f32_16x16x32_bf16 v[24:27], v[162:165], v[204:207], v[24:27]
	v_mfma_f32_16x16x32_bf16 v[0:3], v[170:173], v[204:207], v[0:3]
	v_mfma_f32_16x16x32_bf16 v[72:75], v[162:165], v[222:225], v[72:75]
	s_barrier
	v_mfma_f32_16x16x32_bf16 v[40:43], v[170:173], v[222:225], v[40:43]
	s_setprio 0
	s_add_i32 s84, 0, 0x18000
	s_add_i32 s85, 0, 0x1c000
	v_add_u32_e32 v154, s84, v135
	v_add_u32_e32 v170, s85, v135
	ds_read_b128 v[142:145], v154
	ds_read_b128 v[146:149], v154 offset:1024
	ds_read_b128 v[150:153], v154 offset:2048
	ds_read_b128 v[154:157], v154 offset:3072
	ds_read_b128 v[158:161], v170
	ds_read_b128 v[162:165], v170 offset:1024
	ds_read_b128 v[166:169], v170 offset:2048
	ds_read_b128 v[170:173], v170 offset:3072
	s_add_u32 s58, s58, 0x80000
	s_addc_u32 s59, s59, 0
	s_mov_b32 m0, s67
	ds_read_b128 v[178:181], v194 offset:32768
	ds_read_b128 v[182:185], v194 offset:33792
	ds_read_b128 v[186:189], v194 offset:34816
	ds_read_b128 v[196:199], v194 offset:35840
	ds_read_b128 v[200:203], v194 offset:36864
	ds_read_b128 v[204:207], v194 offset:37888
	ds_read_b128 v[218:221], v194 offset:38912
	ds_read_b128 v[222:225], v194 offset:39936
	global_load_lds_dwordx4 v128, s[58:59]
	s_mov_b32 m0, s68
	s_nop 0
	global_load_lds_dwordx4 v130, s[58:59]
	s_waitcnt vmcnt(8)
	s_waitcnt lgkmcnt(0)
	s_barrier
	s_setprio 1
	s_waitcnt lgkmcnt(0)
	v_mfma_f32_16x16x32_bf16 v[124:127], v[142:145], v[178:181], v[124:127]
	v_mfma_f32_16x16x32_bf16 v[120:123], v[150:153], v[178:181], v[120:123]
	v_mfma_f32_16x16x32_bf16 v[68:71], v[142:145], v[186:189], v[68:71]
	v_mfma_f32_16x16x32_bf16 v[64:67], v[150:153], v[186:189], v[64:67]
	v_mfma_f32_16x16x32_bf16 v[60:63], v[142:145], v[200:203], v[60:63]
	v_mfma_f32_16x16x32_bf16 v[20:23], v[150:153], v[200:203], v[20:23]
	v_mfma_f32_16x16x32_bf16 v[108:111], v[142:145], v[218:221], v[108:111]
	v_mfma_f32_16x16x32_bf16 v[104:107], v[150:153], v[218:221], v[104:107]
	v_mfma_f32_16x16x32_bf16 v[124:127], v[146:149], v[182:185], v[124:127]
	v_mfma_f32_16x16x32_bf16 v[120:123], v[154:157], v[182:185], v[120:123]
	v_mfma_f32_16x16x32_bf16 v[68:71], v[146:149], v[196:199], v[68:71]
	v_mfma_f32_16x16x32_bf16 v[64:67], v[154:157], v[196:199], v[64:67]
	v_mfma_f32_16x16x32_bf16 v[60:63], v[146:149], v[204:207], v[60:63]
	v_mfma_f32_16x16x32_bf16 v[20:23], v[154:157], v[204:207], v[20:23]
	v_mfma_f32_16x16x32_bf16 v[108:111], v[146:149], v[222:225], v[108:111]
	v_mfma_f32_16x16x32_bf16 v[104:107], v[154:157], v[222:225], v[104:107]
	s_setprio 0
	s_setprio 1
	v_mfma_f32_16x16x32_bf16 v[116:119], v[158:161], v[178:181], v[116:119]
	v_mfma_f32_16x16x32_bf16 v[112:115], v[166:169], v[178:181], v[112:115]
	v_mfma_f32_16x16x32_bf16 v[52:55], v[158:161], v[186:189], v[52:55]
	v_mfma_f32_16x16x32_bf16 v[48:51], v[166:169], v[186:189], v[48:51]
	v_mfma_f32_16x16x32_bf16 v[44:47], v[158:161], v[200:203], v[44:47]
	v_mfma_f32_16x16x32_bf16 v[16:19], v[166:169], v[200:203], v[16:19]
	v_mfma_f32_16x16x32_bf16 v[100:103], v[158:161], v[218:221], v[100:103]
	v_mfma_f32_16x16x32_bf16 v[96:99], v[166:169], v[218:221], v[96:99]
	v_mfma_f32_16x16x32_bf16 v[116:119], v[162:165], v[182:185], v[116:119]
	v_mfma_f32_16x16x32_bf16 v[112:115], v[170:173], v[182:185], v[112:115]
	v_mfma_f32_16x16x32_bf16 v[52:55], v[162:165], v[196:199], v[52:55]
	v_mfma_f32_16x16x32_bf16 v[48:51], v[170:173], v[196:199], v[48:51]
	v_mfma_f32_16x16x32_bf16 v[44:47], v[162:165], v[204:207], v[44:47]
	v_mfma_f32_16x16x32_bf16 v[16:19], v[170:173], v[204:207], v[16:19]
	v_mfma_f32_16x16x32_bf16 v[100:103], v[162:165], v[222:225], v[100:103]
	s_barrier
;     __device__ __forceinline__ void operator()(f32x4 (&acc)[2][2][4][2], const Unit& u, int wr, int wc, int fr, int fq, const LAS float* rtab) const {
;         const int c0 = u.pn * 128 + wc * 32 + 8 * fq;
; #pragma unroll
;         for (int ai = 0; ai < 2; ++ai)
; #pragma unroll
;             for (int m = 0; m < 4; ++m) { const float r = rtab[ai * HALF + wr * 64 + m * 16 + fr];
; #pragma unroll
;                 for (int bj = 0; bj < 2; ++bj)
; #pragma unroll
;                     for (int n = 0; n < 2; ++n) acc[ai][bj][m][n] = acc[ai][bj][m][n] * r; }
; #pragma unroll
;         for (int ai = 0; ai < 2; ++ai) {
;             const int blk = (u.pm * BM + ai * HALF + wr * 64) >> 6;
;             if (fr < 2) { bf16_t* rp = raw + ((size_t)blk * 4 + fr) * UP_N + c0;
;                 const f32x4 g0 = acc[ai][0][0][0], g1 = acc[ai][0][0][1], u0 = acc[ai][1][0][0], u1 = acc[ai][1][0][1];
;                 u32x4 w; w.x = cvt_pk_bf16(g0[0], g0[1]); w.y = cvt_pk_bf16(g0[2], g0[3]); w.z = cvt_pk_bf16(g1[0], g1[1]); w.w = cvt_pk_bf16(g1[2], g1[3]); *(u32x4*)rp = w;
;                 w.x = cvt_pk_bf16(u0[0], u0[1]); w.y = cvt_pk_bf16(u0[2], u0[3]); w.z = cvt_pk_bf16(u1[0], u1[1]); w.w = cvt_pk_bf16(u1[2], u1[3]); *(u32x4*)(rp + DFF) = w; }
;             if (fr >= 14) { bf16_t* rp = raw + ((size_t)blk * 4 + (fr - 12)) * UP_N + c0;
;                 const f32x4 g0 = acc[ai][0][3][0], g1 = acc[ai][0][3][1], u0 = acc[ai][1][3][0], u1 = acc[ai][1][3][1];
;                 u32x4 w; w.x = cvt_pk_bf16(g0[0], g0[1]); w.y = cvt_pk_bf16(g0[2], g0[3]); w.z = cvt_pk_bf16(g1[0], g1[1]); w.w = cvt_pk_bf16(g1[2], g1[3]); *(u32x4*)rp = w;
;                 w.x = cvt_pk_bf16(u0[0], u0[1]); w.y = cvt_pk_bf16(u0[2], u0[3]); w.z = cvt_pk_bf16(u1[0], u1[1]); w.w = cvt_pk_bf16(u1[2], u1[3]); *(u32x4*)(rp + DFF) = w; }
;         }
;         u32x2 ypk[2][4];
; #pragma unroll
;         for (int n = 0; n < 2; ++n) {
; template <class Epi, bool KREV = false>
; __device__ __forceinline__ void gemm_phase(LAS unsigned char* lds, const Gemm g, const StaticOrder& S, const Epi& E, int wave_s) {
;     ...
;             PG8_LDA(At, 1, 1); PG8_STAGE(PG8_SB(1, 0), b3, voffB); PG8_STAGE(PG8_SB(1, 1), b3 + bh, voffB); PG8_STAGE(PG8_SA(1, 0), a3, voffA);
;             PG8_WAIT_V(8); PG8_WAIT_L(0); PG8_BAR; PG8_MMA(1, 0, At, B0); PG8_MMA(1, 1, At, B1); PG8_BAR; PG8_SCHED;
;         }
;         if (wr == 0) PG8_BAR;
	v_mfma_f32_16x16x32_bf16 v[96:99], v[170:173], v[222:225], v[96:99]
	s_setprio 0
	s_add_i32 s58, s84, s66
	s_mov_b32 m0, s58
	ds_read_b128 v[178:181], v194 offset:49152
	ds_read_b128 v[182:185], v194 offset:50176
	ds_read_b128 v[186:189], v194 offset:51200
	ds_read_b128 v[196:199], v194 offset:52224
	ds_read_b128 v[200:203], v194 offset:53248
	ds_read_b128 v[204:207], v194 offset:54272
	ds_read_b128 v[218:221], v194 offset:55296
	ds_read_b128 v[222:225], v194 offset:56320
	global_load_lds_dwordx4 v176, s[98:99]
	s_add_i32 m0, s58, 0x2000
	s_add_u32 s56, s56, 0x1600080
	s_addc_u32 s57, s57, 0
	s_add_i32 s58, s85, s66
	global_load_lds_dwordx4 v132, s[98:99]
	s_mov_b32 m0, s58
	s_nop 0
	global_load_lds_dwordx4 v176, s[56:57]
	s_add_i32 m0, s58, 0x2000
	s_nop 0
	global_load_lds_dwordx4 v132, s[56:57]
	s_mov_b32 m0, s70
	s_nop 0
	global_load_lds_dwordx4 v128, s[100:101]
	s_mov_b32 m0, s71
	s_nop 0
	global_load_lds_dwordx4 v130, s[100:101]
	s_waitcnt vmcnt(8)
	s_waitcnt lgkmcnt(0)
	s_barrier
	s_setprio 1
	s_waitcnt lgkmcnt(0)
	v_mfma_f32_16x16x32_bf16 v[92:95], v[142:145], v[178:181], v[92:95]
	v_mfma_f32_16x16x32_bf16 v[88:91], v[150:153], v[178:181], v[88:91]
	v_mfma_f32_16x16x32_bf16 v[36:39], v[142:145], v[186:189], v[36:39]
	v_mfma_f32_16x16x32_bf16 v[12:15], v[150:153], v[186:189], v[12:15]
	v_mfma_f32_16x16x32_bf16 v[32:35], v[142:145], v[200:203], v[32:35]
	v_mfma_f32_16x16x32_bf16 v[4:7], v[150:153], v[200:203], v[4:7]
	v_mfma_f32_16x16x32_bf16 v[76:79], v[142:145], v[218:221], v[76:79]
	v_mfma_f32_16x16x32_bf16 v[56:59], v[150:153], v[218:221], v[56:59]
	v_mfma_f32_16x16x32_bf16 v[92:95], v[146:149], v[182:185], v[92:95]
	v_mfma_f32_16x16x32_bf16 v[88:91], v[154:157], v[182:185], v[88:91]
	v_mfma_f32_16x16x32_bf16 v[36:39], v[146:149], v[196:199], v[36:39]
	v_mfma_f32_16x16x32_bf16 v[12:15], v[154:157], v[196:199], v[12:15]
	v_mfma_f32_16x16x32_bf16 v[32:35], v[146:149], v[204:207], v[32:35]
	v_mfma_f32_16x16x32_bf16 v[4:7], v[154:157], v[204:207], v[4:7]
	v_mfma_f32_16x16x32_bf16 v[76:79], v[146:149], v[222:225], v[76:79]
	v_mfma_f32_16x16x32_bf16 v[56:59], v[154:157], v[222:225], v[56:59]
	s_setprio 0
	s_setprio 1
	v_mfma_f32_16x16x32_bf16 v[84:87], v[158:161], v[178:181], v[84:87]
	v_mfma_f32_16x16x32_bf16 v[80:83], v[166:169], v[178:181], v[80:83]
	v_mfma_f32_16x16x32_bf16 v[28:31], v[158:161], v[186:189], v[28:31]
	v_mfma_f32_16x16x32_bf16 v[8:11], v[166:169], v[186:189], v[8:11]
	v_mfma_f32_16x16x32_bf16 v[24:27], v[158:161], v[200:203], v[24:27]
	v_mfma_f32_16x16x32_bf16 v[0:3], v[166:169], v[200:203], v[0:3]
	v_mfma_f32_16x16x32_bf16 v[72:75], v[158:161], v[218:221], v[72:75]
	v_mfma_f32_16x16x32_bf16 v[40:43], v[166:169], v[218:221], v[40:43]
	v_mfma_f32_16x16x32_bf16 v[84:87], v[162:165], v[182:185], v[84:87]
	v_mfma_f32_16x16x32_bf16 v[80:83], v[170:173], v[182:185], v[80:83]
	v_mfma_f32_16x16x32_bf16 v[28:31], v[162:165], v[196:199], v[28:31]
	v_mfma_f32_16x16x32_bf16 v[8:11], v[170:173], v[196:199], v[8:11]
	s_add_i32 s83, s83, 2
	s_add_u32 s54, s54, 0x100
	s_addc_u32 s55, s55, 0
	v_mfma_f32_16x16x32_bf16 v[24:27], v[162:165], v[204:207], v[24:27]
	s_add_u32 s80, s80, 0x100
	s_addc_u32 s82, s82, 0
	v_mfma_f32_16x16x32_bf16 v[0:3], v[170:173], v[204:207], v[0:3]
	s_cmp_gt_u32 s83, 29
	v_mfma_f32_16x16x32_bf16 v[72:75], v[162:165], v[222:225], v[72:75]
	s_barrier
	v_mfma_f32_16x16x32_bf16 v[40:43], v[170:173], v[222:225], v[40:43]
	s_setprio 0
	s_cbranch_scc0 .LBB0_836
	v_lshl_add_u32 v252, s1, 10, v192
	v_mad_u32_u24 v252, v134, 12, v252
	ds_read_b128 v[228:231], v252
	ds_read_b128 v[232:235], v252 offset:512
	v_lshl_or_b32 v213, s0, 7, v193
	v_lshlrev_b32_e32 v253, 2, v213
	global_load_dwordx4 v[144:147], v253, s[34:35]
	global_load_dwordx4 v[152:155], v253, s[40:41]
	global_load_dwordx4 v[160:163], v253, s[42:43]
	global_load_dwordx4 v[168:171], v253, s[36:37]
	global_load_dwordx4 v[180:183], v253, s[44:45]
	global_load_dwordx4 v[188:191], v253, s[46:47]
	global_load_dwordx4 v[200:203], v253, s[48:49]
	global_load_dwordx4 v[220:223], v253, s[50:51]
	global_load_dwordx4 v[148:151], v253, s[34:35] offset:16
	global_load_dwordx4 v[156:159], v253, s[40:41] offset:16
	global_load_dwordx4 v[164:167], v253, s[42:43] offset:16
	global_load_dwordx4 v[172:175], v253, s[36:37] offset:16
	global_load_dwordx4 v[184:187], v253, s[44:45] offset:16
	global_load_dwordx4 v[196:199], v253, s[46:47] offset:16
	global_load_dwordx4 v[204:207], v253, s[48:49] offset:16
	global_load_dwordx4 v[224:227], v253, s[50:51] offset:16
	s_and_b64 vcc, exec, s[38:39]
	s_cbranch_vccz .LBB0_839
	s_barrier
; __device__ __forceinline__ unsigned cvt_pk_bf16(float lo, float hi) { unsigned r; asm volatile("v_cvt_pk_bf16_f32 %0, %1, %2" : "=v"(r) : "v"(lo), "v"(hi)); return r; }
;     __device__ __forceinline__ void operator()(f32x4 (&acc)[2][2][4][2], const Unit& u, int wr, int wc, int fr, int fq, const LAS float* rtab) const {
;         const int c0 = u.pn * 128 + wc * 32 + 8 * fq;
; #pragma unroll
;         for (int ai = 0; ai < 2; ++ai)
; #pragma unroll
;             for (int m = 0; m < 4; ++m) { const float r = rtab[ai * HALF + wr * 64 + m * 16 + fr];
; #pragma unroll
;                 for (int bj = 0; bj < 2; ++bj)
; #pragma unroll
;                     for (int n = 0; n < 2; ++n) acc[ai][bj][m][n] = acc[ai][bj][m][n] * r; }
; #pragma unroll
;         for (int ai = 0; ai < 2; ++ai) {
;             const int blk = (u.pm * BM + ai * HALF + wr * 64) >> 6;
;             if (fr < 2) { bf16_t* rp = raw + ((size_t)blk * 4 + fr) * UP_N + c0;
;                 const f32x4 g0 = acc[ai][0][0][0], g1 = acc[ai][0][0][1], u0 = acc[ai][1][0][0], u1 = acc[ai][1][0][1];
;                 u32x4 w; w.x = cvt_pk_bf16(g0[0], g0[1]); w.y = cvt_pk_bf16(g0[2], g0[3]); w.z = cvt_pk_bf16(g1[0], g1[1]); w.w = cvt_pk_bf16(g1[2], g1[3]); *(u32x4*)rp = w;
;                 w.x = cvt_pk_bf16(u0[0], u0[1]); w.y = cvt_pk_bf16(u0[2], u0[3]); w.z = cvt_pk_bf16(u1[0], u1[1]); w.w = cvt_pk_bf16(u1[2], u1[3]); *(u32x4*)(rp + DFF) = w; }
.LBB0_839:
	s_waitcnt lgkmcnt(0)
	v_pk_mul_f32 v[124:125], v[124:125], v[228:229] op_sel_hi:[1,0]
	v_pk_mul_f32 v[126:127], v[126:127], v[228:229] op_sel_hi:[1,0]
	v_pk_mul_f32 v[120:121], v[120:121], v[228:229] op_sel_hi:[1,0]
	v_pk_mul_f32 v[122:123], v[122:123], v[228:229] op_sel_hi:[1,0]
	v_pk_mul_f32 v[116:117], v[116:117], v[228:229] op_sel_hi:[1,0]
	v_pk_mul_f32 v[118:119], v[118:119], v[228:229] op_sel_hi:[1,0]
	v_pk_mul_f32 v[112:113], v[112:113], v[228:229] op_sel_hi:[1,0]
	v_pk_mul_f32 v[114:115], v[114:115], v[228:229] op_sel_hi:[1,0]
	v_pk_mul_f32 v[68:69], v[68:69], v[228:229] op_sel:[0,1] op_sel_hi:[1,1]
	v_pk_mul_f32 v[70:71], v[70:71], v[228:229] op_sel:[0,1] op_sel_hi:[1,1]
	v_pk_mul_f32 v[64:65], v[64:65], v[228:229] op_sel:[0,1] op_sel_hi:[1,1]
	v_pk_mul_f32 v[66:67], v[66:67], v[228:229] op_sel:[0,1] op_sel_hi:[1,1]
	v_pk_mul_f32 v[52:53], v[52:53], v[228:229] op_sel:[0,1] op_sel_hi:[1,1]
	v_pk_mul_f32 v[54:55], v[54:55], v[228:229] op_sel:[0,1] op_sel_hi:[1,1]
	v_pk_mul_f32 v[48:49], v[48:49], v[228:229] op_sel:[0,1] op_sel_hi:[1,1]
	v_pk_mul_f32 v[50:51], v[50:51], v[228:229] op_sel:[0,1] op_sel_hi:[1,1]
	v_pk_mul_f32 v[60:61], v[60:61], v[230:231] op_sel_hi:[1,0]
	v_pk_mul_f32 v[62:63], v[62:63], v[230:231] op_sel_hi:[1,0]
	v_pk_mul_f32 v[20:21], v[20:21], v[230:231] op_sel_hi:[1,0]
	v_pk_mul_f32 v[22:23], v[22:23], v[230:231] op_sel_hi:[1,0]
	v_pk_mul_f32 v[44:45], v[44:45], v[230:231] op_sel_hi:[1,0]
	v_pk_mul_f32 v[46:47], v[46:47], v[230:231] op_sel_hi:[1,0]
	v_pk_mul_f32 v[16:17], v[16:17], v[230:231] op_sel_hi:[1,0]
	v_pk_mul_f32 v[18:19], v[18:19], v[230:231] op_sel_hi:[1,0]
	v_pk_mul_f32 v[108:109], v[108:109], v[230:231] op_sel:[0,1] op_sel_hi:[1,1]
	v_pk_mul_f32 v[110:111], v[110:111], v[230:231] op_sel:[0,1] op_sel_hi:[1,1]
	v_pk_mul_f32 v[104:105], v[104:105], v[230:231] op_sel:[0,1] op_sel_hi:[1,1]
	v_pk_mul_f32 v[106:107], v[106:107], v[230:231] op_sel:[0,1] op_sel_hi:[1,1]
	v_pk_mul_f32 v[100:101], v[100:101], v[230:231] op_sel:[0,1] op_sel_hi:[1,1]
	v_pk_mul_f32 v[102:103], v[102:103], v[230:231] op_sel:[0,1] op_sel_hi:[1,1]
	v_pk_mul_f32 v[96:97], v[96:97], v[230:231] op_sel:[0,1] op_sel_hi:[1,1]
	v_pk_mul_f32 v[98:99], v[98:99], v[230:231] op_sel:[0,1] op_sel_hi:[1,1]
	v_pk_mul_f32 v[92:93], v[92:93], v[232:233] op_sel_hi:[1,0]
	v_pk_mul_f32 v[94:95], v[94:95], v[232:233] op_sel_hi:[1,0]
	v_pk_mul_f32 v[88:89], v[88:89], v[232:233] op_sel_hi:[1,0]
	v_pk_mul_f32 v[90:91], v[90:91], v[232:233] op_sel_hi:[1,0]
	v_pk_mul_f32 v[84:85], v[84:85], v[232:233] op_sel_hi:[1,0]
	v_pk_mul_f32 v[86:87], v[86:87], v[232:233] op_sel_hi:[1,0]
	v_pk_mul_f32 v[80:81], v[80:81], v[232:233] op_sel_hi:[1,0]
	v_pk_mul_f32 v[82:83], v[82:83], v[232:233] op_sel_hi:[1,0]
	v_pk_mul_f32 v[36:37], v[36:37], v[232:233] op_sel:[0,1] op_sel_hi:[1,1]
	v_pk_mul_f32 v[38:39], v[38:39], v[232:233] op_sel:[0,1] op_sel_hi:[1,1]
	v_pk_mul_f32 v[12:13], v[12:13], v[232:233] op_sel:[0,1] op_sel_hi:[1,1]
	v_pk_mul_f32 v[14:15], v[14:15], v[232:233] op_sel:[0,1] op_sel_hi:[1,1]
	v_pk_mul_f32 v[28:29], v[28:29], v[232:233] op_sel:[0,1] op_sel_hi:[1,1]
	v_pk_mul_f32 v[30:31], v[30:31], v[232:233] op_sel:[0,1] op_sel_hi:[1,1]
	v_pk_mul_f32 v[8:9], v[8:9], v[232:233] op_sel:[0,1] op_sel_hi:[1,1]
	v_pk_mul_f32 v[10:11], v[10:11], v[232:233] op_sel:[0,1] op_sel_hi:[1,1]
	v_pk_mul_f32 v[32:33], v[32:33], v[234:235] op_sel_hi:[1,0]
	v_pk_mul_f32 v[34:35], v[34:35], v[234:235] op_sel_hi:[1,0]
	v_pk_mul_f32 v[4:5], v[4:5], v[234:235] op_sel_hi:[1,0]
	v_pk_mul_f32 v[6:7], v[6:7], v[234:235] op_sel_hi:[1,0]
	v_pk_mul_f32 v[24:25], v[24:25], v[234:235] op_sel_hi:[1,0]
	v_pk_mul_f32 v[26:27], v[26:27], v[234:235] op_sel_hi:[1,0]
	v_pk_mul_f32 v[0:1], v[0:1], v[234:235] op_sel_hi:[1,0]
	v_pk_mul_f32 v[2:3], v[2:3], v[234:235] op_sel_hi:[1,0]
	v_pk_mul_f32 v[76:77], v[76:77], v[234:235] op_sel:[0,1] op_sel_hi:[1,1]
	v_pk_mul_f32 v[78:79], v[78:79], v[234:235] op_sel:[0,1] op_sel_hi:[1,1]
	v_pk_mul_f32 v[56:57], v[56:57], v[234:235] op_sel:[0,1] op_sel_hi:[1,1]
	v_pk_mul_f32 v[58:59], v[58:59], v[234:235] op_sel:[0,1] op_sel_hi:[1,1]
	v_pk_mul_f32 v[72:73], v[72:73], v[234:235] op_sel:[0,1] op_sel_hi:[1,1]
	v_pk_mul_f32 v[74:75], v[74:75], v[234:235] op_sel:[0,1] op_sel_hi:[1,1]
	v_pk_mul_f32 v[40:41], v[40:41], v[234:235] op_sel:[0,1] op_sel_hi:[1,1]
	v_pk_mul_f32 v[42:43], v[42:43], v[234:235] op_sel:[0,1] op_sel_hi:[1,1]
	v_lshlrev_b32_e32 v235, 1, v213
	s_lshl_b32 s0, s18, 8
	s_add_i32 s0, s0, s69
	v_lshl_add_u32 v234, v134, 2, s0
	v_mul_lo_u32 v234, v234, s89
	v_add_u32_e32 v234, v234, v235
	v_cmp_eq_u32_e64 s[54:55], 0, v134
	v_cmp_eq_u32_e64 s[56:57], 15, v134
	s_lshl_b32 s0, s18, 4
	s_lshr_b32 s1, s69, 4
	s_add_i32 s0, s0, s1
	s_add_i32 s1, s0, 0
	s_mul_i32 s1, s1, s88
	s_add_u32 s58, s30, s1
	s_addc_u32 s59, s31, 0
	s_mov_b64 exec, s[54:55]
	v_cvt_pk_bf16_f32 v244, v124, v125
	v_cvt_pk_bf16_f32 v245, v126, v127
	v_cvt_pk_bf16_f32 v246, v120, v121
	v_cvt_pk_bf16_f32 v247, v122, v123
	v_cvt_pk_bf16_f32 v248, v116, v117
	v_cvt_pk_bf16_f32 v249, v118, v119
	v_cvt_pk_bf16_f32 v250, v112, v113
	v_cvt_pk_bf16_f32 v251, v114, v115
	global_store_dwordx4 v235, v[244:247], s[58:59]
	s_add_u32 s58, s58, 0x2c00
	s_addc_u32 s59, s59, 0
	global_store_dwordx4 v235, v[248:251], s[58:59]
	s_add_i32 s1, s0, 1
	s_mul_i32 s1, s1, s88
	s_add_u32 s58, s30, s1
	s_addc_u32 s59, s31, 0
	s_mov_b64 exec, s[54:55]
	v_cvt_pk_bf16_f32 v236, v68, v69
	v_cvt_pk_bf16_f32 v237, v70, v71
	v_cvt_pk_bf16_f32 v238, v64, v65
	v_cvt_pk_bf16_f32 v239, v66, v67
	v_cvt_pk_bf16_f32 v240, v52, v53
	v_cvt_pk_bf16_f32 v241, v54, v55
	v_cvt_pk_bf16_f32 v242, v48, v49
	v_cvt_pk_bf16_f32 v243, v50, v51
;     __device__ __forceinline__ void operator()(f32x4 (&acc)[2][2][4][2], const Unit& u, int wr, int wc, int fr, int fq, const LAS float* rtab) const {
;     ...
;             const int blk = (u.pm * BM + ai * HALF + wr * 64) >> 6;
;             if (fr < 2) { bf16_t* rp = raw + ((size_t)blk * 4 + fr) * UP_N + c0;
;                 const f32x4 g0 = acc[ai][0][0][0], g1 = acc[ai][0][0][1], u0 = acc[ai][1][0][0], u1 = acc[ai][1][0][1];
;                 u32x4 w; w.x = cvt_pk_bf16(g0[0], g0[1]); w.y = cvt_pk_bf16(g0[2], g0[3]); w.z = cvt_pk_bf16(g1[0], g1[1]); w.w = cvt_pk_bf16(g1[2], g1[3]); *(u32x4*)rp = w;
;                 w.x = cvt_pk_bf16(u0[0], u0[1]); w.y = cvt_pk_bf16(u0[2], u0[3]); w.z = cvt_pk_bf16(u1[0], u1[1]); w.w = cvt_pk_bf16(u1[2], u1[3]); *(u32x4*)(rp + DFF) = w; }
;             if (fr >= 14) { bf16_t* rp = raw + ((size_t)blk * 4 + (fr - 12)) * UP_N + c0;
;                 const f32x4 g0 = acc[ai][0][3][0], g1 = acc[ai][0][3][1], u0 = acc[ai][1][3][0], u1 = acc[ai][1][3][1];
;                 u32x4 w; w.x = cvt_pk_bf16(g0[0], g0[1]); w.y = cvt_pk_bf16(g0[2], g0[3]); w.z = cvt_pk_bf16(g1[0], g1[1]); w.w = cvt_pk_bf16(g1[2], g1[3]); *(u32x4*)rp = w;
;                 w.x = cvt_pk_bf16(u0[0], u0[1]); w.y = cvt_pk_bf16(u0[2], u0[3]); w.z = cvt_pk_bf16(u1[0], u1[1]); w.w = cvt_pk_bf16(u1[2], u1[3]); *(u32x4*)(rp + DFF) = w; }
;         }
;         u32x2 ypk[2][4];
; #pragma unroll
;         for (int n = 0; n < 2; ++n) {
;             const int cn = c0 + 4 * n;
;             const f32x4 wg0 = *(const f32x4*)(cw + cn), wg1 = *(const f32x4*)(cw + UP_N + cn), wg2 = *(const f32x4*)(cw + 2 * UP_N + cn), bg = *(const f32x4*)(cb + cn);
;             const f32x4 wu0 = *(const f32x4*)(cw + DFF + cn), wu1 = *(const f32x4*)(cw + UP_N + DFF + cn), wu2 = *(const f32x4*)(cw + 2 * UP_N + DFF + cn), bu = *(const f32x4*)(cb + DFF + cn);
; #pragma unroll
;             for (int ai = 0; ai < 2; ++ai) {
;                 const int r64 = u.pm * BM + ai * HALF + wr * 64;
; #pragma unroll
;                 for (int m = 0; m < 4; ++m) {
;                     float y[4];
; #pragma unroll
;                     for (int jj = 0; jj < 4; ++jj) {
;                         const float gc = acc[ai][0][m][n][jj], uc = acc[ai][1][m][n][jj];
;                         const float gb = m > 0 ? acc[ai][0][m - 1][n][jj] : 0.f, ga = m < 3 ? acc[ai][0][m + 1][n][jj] : 0.f;
	global_store_dwordx4 v235, v[236:239], s[58:59]
	s_add_u32 s58, s58, 0x2c00
	s_addc_u32 s59, s59, 0
	global_store_dwordx4 v235, v[240:243], s[58:59]
	s_add_i32 s1, s0, 2
	s_mul_i32 s1, s1, s88
	s_add_u32 s58, s30, s1
	s_addc_u32 s59, s31, 0
	s_mov_b64 exec, s[56:57]
	v_cvt_pk_bf16_f32 v244, v60, v61
	v_cvt_pk_bf16_f32 v245, v62, v63
	v_cvt_pk_bf16_f32 v246, v20, v21
	v_cvt_pk_bf16_f32 v247, v22, v23
	v_cvt_pk_bf16_f32 v248, v44, v45
	v_cvt_pk_bf16_f32 v249, v46, v47
	v_cvt_pk_bf16_f32 v250, v16, v17
	v_cvt_pk_bf16_f32 v251, v18, v19
	global_store_dwordx4 v235, v[244:247], s[58:59]
	s_add_u32 s58, s58, 0x2c00
	s_addc_u32 s59, s59, 0
	global_store_dwordx4 v235, v[248:251], s[58:59]
	s_add_i32 s1, s0, 3
	s_mul_i32 s1, s1, s88
	s_add_u32 s58, s30, s1
	s_addc_u32 s59, s31, 0
	s_mov_b64 exec, s[56:57]
	v_cvt_pk_bf16_f32 v236, v108, v109
	v_cvt_pk_bf16_f32 v237, v110, v111
	v_cvt_pk_bf16_f32 v238, v104, v105
	v_cvt_pk_bf16_f32 v239, v106, v107
	v_cvt_pk_bf16_f32 v240, v100, v101
	v_cvt_pk_bf16_f32 v241, v102, v103
	v_cvt_pk_bf16_f32 v242, v96, v97
	v_cvt_pk_bf16_f32 v243, v98, v99
	global_store_dwordx4 v235, v[236:239], s[58:59]
	s_add_u32 s58, s58, 0x2c00
	s_addc_u32 s59, s59, 0
	global_store_dwordx4 v235, v[240:243], s[58:59]
	s_add_i32 s1, s0, 8
	s_mul_i32 s1, s1, s88
	s_add_u32 s58, s30, s1
	s_addc_u32 s59, s31, 0
	s_mov_b64 exec, s[54:55]
	v_cvt_pk_bf16_f32 v244, v92, v93
	v_cvt_pk_bf16_f32 v245, v94, v95
	v_cvt_pk_bf16_f32 v246, v88, v89
	v_cvt_pk_bf16_f32 v247, v90, v91
	v_cvt_pk_bf16_f32 v248, v84, v85
	v_cvt_pk_bf16_f32 v249, v86, v87
	v_cvt_pk_bf16_f32 v250, v80, v81
	v_cvt_pk_bf16_f32 v251, v82, v83
	global_store_dwordx4 v235, v[244:247], s[58:59]
	s_add_u32 s58, s58, 0x2c00
	s_addc_u32 s59, s59, 0
	global_store_dwordx4 v235, v[248:251], s[58:59]
	s_add_i32 s1, s0, 9
	s_mul_i32 s1, s1, s88
	s_add_u32 s58, s30, s1
	s_addc_u32 s59, s31, 0
	s_mov_b64 exec, s[54:55]
	v_cvt_pk_bf16_f32 v236, v36, v37
	v_cvt_pk_bf16_f32 v237, v38, v39
	v_cvt_pk_bf16_f32 v238, v12, v13
	v_cvt_pk_bf16_f32 v239, v14, v15
	v_cvt_pk_bf16_f32 v240, v28, v29
	v_cvt_pk_bf16_f32 v241, v30, v31
	v_cvt_pk_bf16_f32 v242, v8, v9
	v_cvt_pk_bf16_f32 v243, v10, v11
	global_store_dwordx4 v235, v[236:239], s[58:59]
	s_add_u32 s58, s58, 0x2c00
	s_addc_u32 s59, s59, 0
	global_store_dwordx4 v235, v[240:243], s[58:59]
	s_add_i32 s1, s0, 10
	s_mul_i32 s1, s1, s88
	s_add_u32 s58, s30, s1
	s_addc_u32 s59, s31, 0
	s_mov_b64 exec, s[56:57]
	v_cvt_pk_bf16_f32 v244, v32, v33
	v_cvt_pk_bf16_f32 v245, v34, v35
	v_cvt_pk_bf16_f32 v246, v4, v5
	v_cvt_pk_bf16_f32 v247, v6, v7
	v_cvt_pk_bf16_f32 v248, v24, v25
	v_cvt_pk_bf16_f32 v249, v26, v27
	v_cvt_pk_bf16_f32 v250, v0, v1
	v_cvt_pk_bf16_f32 v251, v2, v3
	global_store_dwordx4 v235, v[244:247], s[58:59]
	s_add_u32 s58, s58, 0x2c00
	s_addc_u32 s59, s59, 0
	global_store_dwordx4 v235, v[248:251], s[58:59]
	s_add_i32 s1, s0, 11
	s_mul_i32 s1, s1, s88
	s_add_u32 s58, s30, s1
	s_addc_u32 s59, s31, 0
	s_mov_b64 exec, s[56:57]
	v_cvt_pk_bf16_f32 v236, v76, v77
	v_cvt_pk_bf16_f32 v237, v78, v79
	v_cvt_pk_bf16_f32 v238, v56, v57
	v_cvt_pk_bf16_f32 v239, v58, v59
	v_cvt_pk_bf16_f32 v240, v72, v73
	v_cvt_pk_bf16_f32 v241, v74, v75
	v_cvt_pk_bf16_f32 v242, v40, v41
	v_cvt_pk_bf16_f32 v243, v42, v43
	global_store_dwordx4 v235, v[236:239], s[58:59]
	s_add_u32 s58, s58, 0x2c00
	s_addc_u32 s59, s59, 0
	global_store_dwordx4 v235, v[240:243], s[58:59]
	s_mov_b64 exec, -1
	s_waitcnt vmcnt(24)
	s_mov_b32 s54, 0xbfb8aa3b
	s_mov_b32 s56, 1.0
	v_pk_fma_f32 v[142:143], v[152:153], v[124:125], v[168:169]
	v_pk_fma_f32 v[178:179], v[152:153], v[68:69], v[168:169]
	v_pk_fma_f32 v[210:211], v[152:153], v[60:61], v[168:169]
	v_pk_fma_f32 v[212:213], v[152:153], v[108:109], v[168:169]
	v_pk_fma_f32 v[142:143], v[160:161], v[68:69], v[142:143]
	v_pk_fma_f32 v[178:179], v[144:145], v[124:125], v[178:179]
	v_pk_fma_f32 v[210:211], v[144:145], v[68:69], v[210:211]
	v_pk_fma_f32 v[212:213], v[144:145], v[60:61], v[212:213]
	v_pk_fma_f32 v[178:179], v[160:161], v[60:61], v[178:179]
	v_pk_fma_f32 v[210:211], v[160:161], v[108:109], v[210:211]
	v_fmac_f32_dpp v142, v108, v144 row_shr:1 row_mask:0xf bank_mask:0xf bound_ctrl:1
	v_fmac_f32_dpp v212, v124, v160 row_shl:1 row_mask:0xf bank_mask:0xf bound_ctrl:1
	v_fmac_f32_dpp v143, v109, v145 row_shr:1 row_mask:0xf bank_mask:0xf bound_ctrl:1
	v_fmac_f32_dpp v213, v125, v161 row_shl:1 row_mask:0xf bank_mask:0xf bound_ctrl:1
	v_pk_mul_f32 v[218:219], v[142:143], s[54:55] op_sel_hi:[1,0]
	v_pk_mul_f32 v[252:253], v[178:179], s[54:55] op_sel_hi:[1,0]
	v_pk_mul_f32 v[228:229], v[210:211], s[54:55] op_sel_hi:[1,0]
	v_pk_mul_f32 v[230:231], v[212:213], s[54:55] op_sel_hi:[1,0]
	v_exp_f32_e32 v218, v218
	v_exp_f32_e32 v219, v219
	v_exp_f32_e32 v252, v252
	v_exp_f32_e32 v253, v253
	v_exp_f32_e32 v228, v228
	v_exp_f32_e32 v229, v229
	v_exp_f32_e32 v230, v230
	v_exp_f32_e32 v231, v231
	v_pk_add_f32 v[218:219], v[218:219], s[56:57] op_sel_hi:[1,0]
	v_pk_add_f32 v[252:253], v[252:253], s[56:57] op_sel_hi:[1,0]
	v_pk_add_f32 v[228:229], v[228:229], s[56:57] op_sel_hi:[1,0]
	v_pk_add_f32 v[230:231], v[230:231], s[56:57] op_sel_hi:[1,0]
	v_rcp_f32_e32 v218, v218
	v_rcp_f32_e32 v219, v219
	v_rcp_f32_e32 v252, v252
	v_rcp_f32_e32 v253, v253
	v_rcp_f32_e32 v228, v228
	v_rcp_f32_e32 v229, v229
	v_rcp_f32_e32 v230, v230
	v_rcp_f32_e32 v231, v231
	v_pk_mul_f32 v[142:143], v[142:143], v[218:219]
	v_pk_mul_f32 v[178:179], v[178:179], v[252:253]
	v_pk_mul_f32 v[210:211], v[210:211], v[228:229]
	v_pk_mul_f32 v[212:213], v[212:213], v[230:231]
	v_pk_fma_f32 v[218:219], v[188:189], v[116:117], v[220:221]
	v_pk_fma_f32 v[252:253], v[188:189], v[52:53], v[220:221]
;     __device__ __forceinline__ void operator()(f32x4 (&acc)[2][2][4][2], const Unit& u, int wr, int wc, int fr, int fq, const LAS float* rtab) const {
;     ...
;         for (int n = 0; n < 2; ++n) {
;             const int cn = c0 + 4 * n;
;             const f32x4 wg0 = *(const f32x4*)(cw + cn), wg1 = *(const f32x4*)(cw + UP_N + cn), wg2 = *(const f32x4*)(cw + 2 * UP_N + cn), bg = *(const f32x4*)(cb + cn);
;             const f32x4 wu0 = *(const f32x4*)(cw + DFF + cn), wu1 = *(const f32x4*)(cw + UP_N + DFF + cn), wu2 = *(const f32x4*)(cw + 2 * UP_N + DFF + cn), bu = *(const f32x4*)(cb + DFF + cn);
; #pragma unroll
;             for (int ai = 0; ai < 2; ++ai) {
;                 const int r64 = u.pm * BM + ai * HALF + wr * 64;
; #pragma unroll
;                 for (int m = 0; m < 4; ++m) {
;                     float y[4];
; #pragma unroll
;                     for (int jj = 0; jj < 4; ++jj) {
;                         const float gc = acc[ai][0][m][n][jj], uc = acc[ai][1][m][n][jj];
;                         const float gb = m > 0 ? acc[ai][0][m - 1][n][jj] : 0.f, ga = m < 3 ? acc[ai][0][m + 1][n][jj] : 0.f;
;                         const float ub = m > 0 ? acc[ai][1][m - 1][n][jj] : 0.f, ua = m < 3 ? acc[ai][1][m + 1][n][jj] : 0.f;
;                         const float gp = dppz<0x111>(gc) + dppz<0x10F>(gb), gn = dppz<0x101>(gc) + dppz<0x11F>(ga);
;                         const float up = dppz<0x111>(uc) + dppz<0x10F>(ub), un = dppz<0x101>(uc) + dppz<0x11F>(ua);
;                         const float hg = wg0[jj] * gp + wg1[jj] * gc + wg2[jj] * gn + bg[jj];
;                         const float hu = wu0[jj] * up + wu1[jj] * uc + wu2[jj] * un + bu[jj];
;                         const float sg = __builtin_amdgcn_rcpf(1.f + __builtin_amdgcn_exp2f(-1.4426950408889634f * hg));
;                         y[jj] = hg * sg * hu; }
;                     u32x2 pk; pk.x = cvt_pk_bf16(y[0], y[1]); pk.y = cvt_pk_bf16(y[2], y[3]);
;                     if (n == 0) ypk[ai][m] = pk;
;                     else {
;                         const bool deferred = (m == 0 && fr == 0) || (m == 3 && fr == 15);
;                         if (!deferred) { u32x4 w; w.x = ypk[ai][m].x; w.y = ypk[ai][m].y; w.z = pk.x; w.w = pk.y; *(u32x4*)(act + (size_t)(r64 + m * 16 + fr) * DFF + c0) = w; } }
	v_pk_fma_f32 v[228:229], v[188:189], v[44:45], v[220:221]
	v_pk_fma_f32 v[230:231], v[188:189], v[100:101], v[220:221]
	v_pk_fma_f32 v[218:219], v[200:201], v[52:53], v[218:219]
	v_pk_fma_f32 v[252:253], v[180:181], v[116:117], v[252:253]
	v_pk_fma_f32 v[228:229], v[180:181], v[52:53], v[228:229]
	v_pk_fma_f32 v[230:231], v[180:181], v[44:45], v[230:231]
	v_pk_fma_f32 v[252:253], v[200:201], v[44:45], v[252:253]
	v_pk_fma_f32 v[228:229], v[200:201], v[100:101], v[228:229]
	v_fmac_f32_dpp v218, v100, v180 row_shr:1 row_mask:0xf bank_mask:0xf bound_ctrl:1
	v_fmac_f32_dpp v230, v116, v200 row_shl:1 row_mask:0xf bank_mask:0xf bound_ctrl:1
	v_fmac_f32_dpp v219, v101, v181 row_shr:1 row_mask:0xf bank_mask:0xf bound_ctrl:1
	v_fmac_f32_dpp v231, v117, v201 row_shl:1 row_mask:0xf bank_mask:0xf bound_ctrl:1
	v_pk_mul_f32 v[142:143], v[142:143], v[218:219]
	v_pk_mul_f32 v[178:179], v[178:179], v[252:253]
	v_pk_mul_f32 v[210:211], v[210:211], v[228:229]
	v_pk_mul_f32 v[212:213], v[212:213], v[230:231]
	v_cvt_pk_bf16_f32 v236, v142, v143
	v_cvt_pk_bf16_f32 v240, v178, v179
	v_cvt_pk_bf16_f32 v244, v210, v211
	v_cvt_pk_bf16_f32 v248, v212, v213
	v_pk_fma_f32 v[142:143], v[154:155], v[126:127], v[170:171]
	v_pk_fma_f32 v[178:179], v[154:155], v[70:71], v[170:171]
	v_pk_fma_f32 v[210:211], v[154:155], v[62:63], v[170:171]
	v_pk_fma_f32 v[212:213], v[154:155], v[110:111], v[170:171]
	v_pk_fma_f32 v[142:143], v[162:163], v[70:71], v[142:143]
	v_pk_fma_f32 v[178:179], v[146:147], v[126:127], v[178:179]
	v_pk_fma_f32 v[210:211], v[146:147], v[70:71], v[210:211]
	v_pk_fma_f32 v[212:213], v[146:147], v[62:63], v[212:213]
	v_pk_fma_f32 v[178:179], v[162:163], v[62:63], v[178:179]
	v_pk_fma_f32 v[210:211], v[162:163], v[110:111], v[210:211]
	v_fmac_f32_dpp v142, v110, v146 row_shr:1 row_mask:0xf bank_mask:0xf bound_ctrl:1
	v_fmac_f32_dpp v212, v126, v162 row_shl:1 row_mask:0xf bank_mask:0xf bound_ctrl:1
	v_fmac_f32_dpp v143, v111, v147 row_shr:1 row_mask:0xf bank_mask:0xf bound_ctrl:1
	v_fmac_f32_dpp v213, v127, v163 row_shl:1 row_mask:0xf bank_mask:0xf bound_ctrl:1
	v_pk_mul_f32 v[218:219], v[142:143], s[54:55] op_sel_hi:[1,0]
	v_pk_mul_f32 v[252:253], v[178:179], s[54:55] op_sel_hi:[1,0]
	v_pk_mul_f32 v[228:229], v[210:211], s[54:55] op_sel_hi:[1,0]
	v_pk_mul_f32 v[230:231], v[212:213], s[54:55] op_sel_hi:[1,0]
	v_exp_f32_e32 v218, v218
	v_exp_f32_e32 v219, v219
	v_exp_f32_e32 v252, v252
	v_exp_f32_e32 v253, v253
	v_exp_f32_e32 v228, v228
	v_exp_f32_e32 v229, v229
	v_exp_f32_e32 v230, v230
	v_exp_f32_e32 v231, v231
	v_pk_add_f32 v[218:219], v[218:219], s[56:57] op_sel_hi:[1,0]
	v_pk_add_f32 v[252:253], v[252:253], s[56:57] op_sel_hi:[1,0]
	v_pk_add_f32 v[228:229], v[228:229], s[56:57] op_sel_hi:[1,0]
	v_pk_add_f32 v[230:231], v[230:231], s[56:57] op_sel_hi:[1,0]
	v_rcp_f32_e32 v218, v218
	v_rcp_f32_e32 v219, v219
	v_rcp_f32_e32 v252, v252
	v_rcp_f32_e32 v253, v253
	v_rcp_f32_e32 v228, v228
	v_rcp_f32_e32 v229, v229
	v_rcp_f32_e32 v230, v230
	v_rcp_f32_e32 v231, v231
	v_pk_mul_f32 v[142:143], v[142:143], v[218:219]
	v_pk_mul_f32 v[178:179], v[178:179], v[252:253]
	v_pk_mul_f32 v[210:211], v[210:211], v[228:229]
	v_pk_mul_f32 v[212:213], v[212:213], v[230:231]
	v_pk_fma_f32 v[218:219], v[190:191], v[118:119], v[222:223]
	v_pk_fma_f32 v[252:253], v[190:191], v[54:55], v[222:223]
	v_pk_fma_f32 v[228:229], v[190:191], v[46:47], v[222:223]
	v_pk_fma_f32 v[230:231], v[190:191], v[102:103], v[222:223]
	v_pk_fma_f32 v[218:219], v[202:203], v[54:55], v[218:219]
	v_pk_fma_f32 v[252:253], v[182:183], v[118:119], v[252:253]
	v_pk_fma_f32 v[228:229], v[182:183], v[54:55], v[228:229]
	v_pk_fma_f32 v[230:231], v[182:183], v[46:47], v[230:231]
	v_pk_fma_f32 v[252:253], v[202:203], v[46:47], v[252:253]
	v_pk_fma_f32 v[228:229], v[202:203], v[102:103], v[228:229]
	v_fmac_f32_dpp v218, v102, v182 row_shr:1 row_mask:0xf bank_mask:0xf bound_ctrl:1
	v_fmac_f32_dpp v230, v118, v202 row_shl:1 row_mask:0xf bank_mask:0xf bound_ctrl:1
	v_fmac_f32_dpp v219, v103, v183 row_shr:1 row_mask:0xf bank_mask:0xf bound_ctrl:1
	v_fmac_f32_dpp v231, v119, v203 row_shl:1 row_mask:0xf bank_mask:0xf bound_ctrl:1
	v_pk_mul_f32 v[142:143], v[142:143], v[218:219]
	v_pk_mul_f32 v[178:179], v[178:179], v[252:253]
	v_pk_mul_f32 v[210:211], v[210:211], v[228:229]
	v_pk_mul_f32 v[212:213], v[212:213], v[230:231]
	v_cvt_pk_bf16_f32 v237, v142, v143
	v_cvt_pk_bf16_f32 v241, v178, v179
	v_cvt_pk_bf16_f32 v245, v210, v211
	v_cvt_pk_bf16_f32 v249, v212, v213
	s_waitcnt vmcnt(16)
; __device__ __forceinline__ unsigned cvt_pk_bf16(float lo, float hi) { unsigned r; asm volatile("v_cvt_pk_bf16_f32 %0, %1, %2" : "=v"(r) : "v"(lo), "v"(hi)); return r; }
; template <int CTRL> __device__ __forceinline__ float dppz(float v) { return __int_as_float(__builtin_amdgcn_update_dpp(0, __float_as_int(v), CTRL, 0xf, 0xf, true)); }
;     __device__ __forceinline__ void operator()(f32x4 (&acc)[2][2][4][2], const Unit& u, int wr, int wc, int fr, int fq, const LAS float* rtab) const {
;     ...
;                 for (int m = 0; m < 4; ++m) {
;                     float y[4];
; #pragma unroll
;                     for (int jj = 0; jj < 4; ++jj) {
;                         const float gc = acc[ai][0][m][n][jj], uc = acc[ai][1][m][n][jj];
;                         const float gb = m > 0 ? acc[ai][0][m - 1][n][jj] : 0.f, ga = m < 3 ? acc[ai][0][m + 1][n][jj] : 0.f;
;                         const float ub = m > 0 ? acc[ai][1][m - 1][n][jj] : 0.f, ua = m < 3 ? acc[ai][1][m + 1][n][jj] : 0.f;
;                         const float gp = dppz<0x111>(gc) + dppz<0x10F>(gb), gn = dppz<0x101>(gc) + dppz<0x11F>(ga);
;                         const float up = dppz<0x111>(uc) + dppz<0x10F>(ub), un = dppz<0x101>(uc) + dppz<0x11F>(ua);
;                         const float hg = wg0[jj] * gp + wg1[jj] * gc + wg2[jj] * gn + bg[jj];
;                         const float hu = wu0[jj] * up + wu1[jj] * uc + wu2[jj] * un + bu[jj];
;                         const float sg = __builtin_amdgcn_rcpf(1.f + __builtin_amdgcn_exp2f(-1.4426950408889634f * hg));
;                         y[jj] = hg * sg * hu; }
;                     u32x2 pk; pk.x = cvt_pk_bf16(y[0], y[1]); pk.y = cvt_pk_bf16(y[2], y[3]);
;                     if (n == 0) ypk[ai][m] = pk;
;                     else {
;                         const bool deferred = (m == 0 && fr == 0) || (m == 3 && fr == 15);
;                         if (!deferred) { u32x4 w; w.x = ypk[ai][m].x; w.y = ypk[ai][m].y; w.z = pk.x; w.w = pk.y; *(u32x4*)(act + (size_t)(r64 + m * 16 + fr) * DFF + c0) = w; } }
	v_pk_fma_f32 v[142:143], v[156:157], v[120:121], v[172:173]
	v_pk_fma_f32 v[178:179], v[156:157], v[64:65], v[172:173]
	v_pk_fma_f32 v[210:211], v[156:157], v[20:21], v[172:173]
	v_pk_fma_f32 v[212:213], v[156:157], v[104:105], v[172:173]
	v_pk_fma_f32 v[142:143], v[164:165], v[64:65], v[142:143]
	v_pk_fma_f32 v[178:179], v[148:149], v[120:121], v[178:179]
	v_pk_fma_f32 v[210:211], v[148:149], v[64:65], v[210:211]
	v_pk_fma_f32 v[212:213], v[148:149], v[20:21], v[212:213]
	v_pk_fma_f32 v[178:179], v[164:165], v[20:21], v[178:179]
	v_pk_fma_f32 v[210:211], v[164:165], v[104:105], v[210:211]
	v_fmac_f32_dpp v142, v104, v148 row_shr:1 row_mask:0xf bank_mask:0xf bound_ctrl:1
	v_fmac_f32_dpp v212, v120, v164 row_shl:1 row_mask:0xf bank_mask:0xf bound_ctrl:1
	v_fmac_f32_dpp v143, v105, v149 row_shr:1 row_mask:0xf bank_mask:0xf bound_ctrl:1
	v_fmac_f32_dpp v213, v121, v165 row_shl:1 row_mask:0xf bank_mask:0xf bound_ctrl:1
	v_pk_mul_f32 v[218:219], v[142:143], s[54:55] op_sel_hi:[1,0]
	v_pk_mul_f32 v[252:253], v[178:179], s[54:55] op_sel_hi:[1,0]
	v_pk_mul_f32 v[228:229], v[210:211], s[54:55] op_sel_hi:[1,0]
	v_pk_mul_f32 v[230:231], v[212:213], s[54:55] op_sel_hi:[1,0]
	v_exp_f32_e32 v218, v218
	v_exp_f32_e32 v219, v219
	v_exp_f32_e32 v252, v252
	v_exp_f32_e32 v253, v253
	v_exp_f32_e32 v228, v228
	v_exp_f32_e32 v229, v229
	v_exp_f32_e32 v230, v230
	v_exp_f32_e32 v231, v231
	v_pk_add_f32 v[218:219], v[218:219], s[56:57] op_sel_hi:[1,0]
	v_pk_add_f32 v[252:253], v[252:253], s[56:57] op_sel_hi:[1,0]
	v_pk_add_f32 v[228:229], v[228:229], s[56:57] op_sel_hi:[1,0]
	v_pk_add_f32 v[230:231], v[230:231], s[56:57] op_sel_hi:[1,0]
	v_rcp_f32_e32 v218, v218
	v_rcp_f32_e32 v219, v219
	v_rcp_f32_e32 v252, v252
	v_rcp_f32_e32 v253, v253
	v_rcp_f32_e32 v228, v228
	v_rcp_f32_e32 v229, v229
	v_rcp_f32_e32 v230, v230
	v_rcp_f32_e32 v231, v231
	v_pk_mul_f32 v[142:143], v[142:143], v[218:219]
	v_pk_mul_f32 v[178:179], v[178:179], v[252:253]
	v_pk_mul_f32 v[210:211], v[210:211], v[228:229]
	v_pk_mul_f32 v[212:213], v[212:213], v[230:231]
	v_pk_fma_f32 v[218:219], v[196:197], v[112:113], v[224:225]
	v_pk_fma_f32 v[252:253], v[196:197], v[48:49], v[224:225]
	v_pk_fma_f32 v[228:229], v[196:197], v[16:17], v[224:225]
	v_pk_fma_f32 v[230:231], v[196:197], v[96:97], v[224:225]
	v_pk_fma_f32 v[218:219], v[204:205], v[48:49], v[218:219]
	v_pk_fma_f32 v[252:253], v[184:185], v[112:113], v[252:253]
	v_pk_fma_f32 v[228:229], v[184:185], v[48:49], v[228:229]
	v_pk_fma_f32 v[230:231], v[184:185], v[16:17], v[230:231]
	v_pk_fma_f32 v[252:253], v[204:205], v[16:17], v[252:253]
	v_pk_fma_f32 v[228:229], v[204:205], v[96:97], v[228:229]
	v_fmac_f32_dpp v218, v96, v184 row_shr:1 row_mask:0xf bank_mask:0xf bound_ctrl:1
	v_fmac_f32_dpp v230, v112, v204 row_shl:1 row_mask:0xf bank_mask:0xf bound_ctrl:1
	v_fmac_f32_dpp v219, v97, v185 row_shr:1 row_mask:0xf bank_mask:0xf bound_ctrl:1
	v_fmac_f32_dpp v231, v113, v205 row_shl:1 row_mask:0xf bank_mask:0xf bound_ctrl:1
	v_pk_mul_f32 v[142:143], v[142:143], v[218:219]
	v_pk_mul_f32 v[178:179], v[178:179], v[252:253]
	v_pk_mul_f32 v[210:211], v[210:211], v[228:229]
	v_pk_mul_f32 v[212:213], v[212:213], v[230:231]
	v_cvt_pk_bf16_f32 v238, v142, v143
	v_cvt_pk_bf16_f32 v242, v178, v179
	v_cvt_pk_bf16_f32 v246, v210, v211
	v_cvt_pk_bf16_f32 v250, v212, v213
	v_pk_fma_f32 v[142:143], v[158:159], v[122:123], v[174:175]
	v_pk_fma_f32 v[178:179], v[158:159], v[66:67], v[174:175]
	v_pk_fma_f32 v[210:211], v[158:159], v[22:23], v[174:175]
	v_pk_fma_f32 v[212:213], v[158:159], v[106:107], v[174:175]
	v_pk_fma_f32 v[142:143], v[166:167], v[66:67], v[142:143]
	v_pk_fma_f32 v[178:179], v[150:151], v[122:123], v[178:179]
	v_pk_fma_f32 v[210:211], v[150:151], v[66:67], v[210:211]
	v_pk_fma_f32 v[212:213], v[150:151], v[22:23], v[212:213]
	v_pk_fma_f32 v[178:179], v[166:167], v[22:23], v[178:179]
	v_pk_fma_f32 v[210:211], v[166:167], v[106:107], v[210:211]
	v_fmac_f32_dpp v142, v106, v150 row_shr:1 row_mask:0xf bank_mask:0xf bound_ctrl:1
	v_fmac_f32_dpp v212, v122, v166 row_shl:1 row_mask:0xf bank_mask:0xf bound_ctrl:1
	v_fmac_f32_dpp v143, v107, v151 row_shr:1 row_mask:0xf bank_mask:0xf bound_ctrl:1
	v_fmac_f32_dpp v213, v123, v167 row_shl:1 row_mask:0xf bank_mask:0xf bound_ctrl:1
	v_pk_mul_f32 v[218:219], v[142:143], s[54:55] op_sel_hi:[1,0]
	v_pk_mul_f32 v[252:253], v[178:179], s[54:55] op_sel_hi:[1,0]
	v_pk_mul_f32 v[228:229], v[210:211], s[54:55] op_sel_hi:[1,0]
	v_pk_mul_f32 v[230:231], v[212:213], s[54:55] op_sel_hi:[1,0]
	v_exp_f32_e32 v218, v218
	v_exp_f32_e32 v219, v219
	v_exp_f32_e32 v252, v252
	v_exp_f32_e32 v253, v253
	v_exp_f32_e32 v228, v228
	v_exp_f32_e32 v229, v229
	v_exp_f32_e32 v230, v230
	v_exp_f32_e32 v231, v231
	v_pk_add_f32 v[218:219], v[218:219], s[56:57] op_sel_hi:[1,0]
	v_pk_add_f32 v[252:253], v[252:253], s[56:57] op_sel_hi:[1,0]
	v_pk_add_f32 v[228:229], v[228:229], s[56:57] op_sel_hi:[1,0]
	v_pk_add_f32 v[230:231], v[230:231], s[56:57] op_sel_hi:[1,0]
	v_rcp_f32_e32 v218, v218
	v_rcp_f32_e32 v219, v219
	v_rcp_f32_e32 v252, v252
	v_rcp_f32_e32 v253, v253
	v_rcp_f32_e32 v228, v228
	v_rcp_f32_e32 v229, v229
	v_rcp_f32_e32 v230, v230
	v_rcp_f32_e32 v231, v231
	v_pk_mul_f32 v[142:143], v[142:143], v[218:219]
	v_pk_mul_f32 v[178:179], v[178:179], v[252:253]
	v_pk_mul_f32 v[210:211], v[210:211], v[228:229]
	v_pk_mul_f32 v[212:213], v[212:213], v[230:231]
	v_pk_fma_f32 v[218:219], v[198:199], v[114:115], v[226:227]
	v_pk_fma_f32 v[252:253], v[198:199], v[50:51], v[226:227]
	v_pk_fma_f32 v[228:229], v[198:199], v[18:19], v[226:227]
	v_pk_fma_f32 v[230:231], v[198:199], v[98:99], v[226:227]
	v_pk_fma_f32 v[218:219], v[206:207], v[50:51], v[218:219]
; __device__ __forceinline__ unsigned cvt_pk_bf16(float lo, float hi) { unsigned r; asm volatile("v_cvt_pk_bf16_f32 %0, %1, %2" : "=v"(r) : "v"(lo), "v"(hi)); return r; }
; template <int CTRL> __device__ __forceinline__ float dppz(float v) { return __int_as_float(__builtin_amdgcn_update_dpp(0, __float_as_int(v), CTRL, 0xf, 0xf, true)); }
;     __device__ __forceinline__ void operator()(f32x4 (&acc)[2][2][4][2], const Unit& u, int wr, int wc, int fr, int fq, const LAS float* rtab) const {
;     ...
;                 for (int m = 0; m < 4; ++m) {
;                     float y[4];
; #pragma unroll
;                     for (int jj = 0; jj < 4; ++jj) {
;                         const float gc = acc[ai][0][m][n][jj], uc = acc[ai][1][m][n][jj];
;                         const float gb = m > 0 ? acc[ai][0][m - 1][n][jj] : 0.f, ga = m < 3 ? acc[ai][0][m + 1][n][jj] : 0.f;
;                         const float ub = m > 0 ? acc[ai][1][m - 1][n][jj] : 0.f, ua = m < 3 ? acc[ai][1][m + 1][n][jj] : 0.f;
;                         const float gp = dppz<0x111>(gc) + dppz<0x10F>(gb), gn = dppz<0x101>(gc) + dppz<0x11F>(ga);
;                         const float up = dppz<0x111>(uc) + dppz<0x10F>(ub), un = dppz<0x101>(uc) + dppz<0x11F>(ua);
;                         const float hg = wg0[jj] * gp + wg1[jj] * gc + wg2[jj] * gn + bg[jj];
;                         const float hu = wu0[jj] * up + wu1[jj] * uc + wu2[jj] * un + bu[jj];
;                         const float sg = __builtin_amdgcn_rcpf(1.f + __builtin_amdgcn_exp2f(-1.4426950408889634f * hg));
;                         y[jj] = hg * sg * hu; }
;                     u32x2 pk; pk.x = cvt_pk_bf16(y[0], y[1]); pk.y = cvt_pk_bf16(y[2], y[3]);
;                     if (n == 0) ypk[ai][m] = pk;
;                     else {
;                         const bool deferred = (m == 0 && fr == 0) || (m == 3 && fr == 15);
;                         if (!deferred) { u32x4 w; w.x = ypk[ai][m].x; w.y = ypk[ai][m].y; w.z = pk.x; w.w = pk.y; *(u32x4*)(act + (size_t)(r64 + m * 16 + fr) * DFF + c0) = w; } }
	v_pk_fma_f32 v[252:253], v[186:187], v[114:115], v[252:253]
	v_pk_fma_f32 v[228:229], v[186:187], v[50:51], v[228:229]
	v_pk_fma_f32 v[230:231], v[186:187], v[18:19], v[230:231]
	v_pk_fma_f32 v[252:253], v[206:207], v[18:19], v[252:253]
	v_pk_fma_f32 v[228:229], v[206:207], v[98:99], v[228:229]
	v_fmac_f32_dpp v218, v98, v186 row_shr:1 row_mask:0xf bank_mask:0xf bound_ctrl:1
	v_fmac_f32_dpp v230, v114, v206 row_shl:1 row_mask:0xf bank_mask:0xf bound_ctrl:1
	v_fmac_f32_dpp v219, v99, v187 row_shr:1 row_mask:0xf bank_mask:0xf bound_ctrl:1
	v_fmac_f32_dpp v231, v115, v207 row_shl:1 row_mask:0xf bank_mask:0xf bound_ctrl:1
	v_pk_mul_f32 v[142:143], v[142:143], v[218:219]
	v_pk_mul_f32 v[178:179], v[178:179], v[252:253]
	v_pk_mul_f32 v[210:211], v[210:211], v[228:229]
	v_pk_mul_f32 v[212:213], v[212:213], v[230:231]
	v_cvt_pk_bf16_f32 v239, v142, v143
	v_cvt_pk_bf16_f32 v243, v178, v179
	v_cvt_pk_bf16_f32 v247, v210, v211
	v_cvt_pk_bf16_f32 v251, v212, v213
	s_mov_b64 s[58:59], s[28:29]
	s_mov_b64 exec, s[12:13]
	global_store_dwordx4 v234, v[236:239], s[58:59]
	s_mov_b64 exec, -1
	s_add_u32 s58, s28, 0x2c00
	s_addc_u32 s59, s29, 0
	global_store_dwordx4 v234, v[240:243], s[58:59]
	s_add_u32 s58, s28, 0x5800
	s_addc_u32 s59, s29, 0
	global_store_dwordx4 v234, v[244:247], s[58:59]
	s_add_u32 s58, s28, 0x8400
	s_addc_u32 s59, s29, 0
	s_mov_b64 exec, s[10:11]
	global_store_dwordx4 v234, v[248:251], s[58:59]
	s_mov_b64 exec, -1
	v_pk_fma_f32 v[142:143], v[152:153], v[92:93], v[168:169]
	v_pk_fma_f32 v[178:179], v[152:153], v[36:37], v[168:169]
	v_pk_fma_f32 v[210:211], v[152:153], v[32:33], v[168:169]
	v_pk_fma_f32 v[212:213], v[152:153], v[76:77], v[168:169]
	v_pk_fma_f32 v[142:143], v[160:161], v[36:37], v[142:143]
	v_pk_fma_f32 v[178:179], v[144:145], v[92:93], v[178:179]
	v_pk_fma_f32 v[210:211], v[144:145], v[36:37], v[210:211]
	v_pk_fma_f32 v[212:213], v[144:145], v[32:33], v[212:213]
	v_pk_fma_f32 v[178:179], v[160:161], v[32:33], v[178:179]
	v_pk_fma_f32 v[210:211], v[160:161], v[76:77], v[210:211]
	v_fmac_f32_dpp v142, v76, v144 row_shr:1 row_mask:0xf bank_mask:0xf bound_ctrl:1
	v_fmac_f32_dpp v212, v92, v160 row_shl:1 row_mask:0xf bank_mask:0xf bound_ctrl:1
	v_fmac_f32_dpp v143, v77, v145 row_shr:1 row_mask:0xf bank_mask:0xf bound_ctrl:1
	v_fmac_f32_dpp v213, v93, v161 row_shl:1 row_mask:0xf bank_mask:0xf bound_ctrl:1
	v_pk_mul_f32 v[218:219], v[142:143], s[54:55] op_sel_hi:[1,0]
	v_pk_mul_f32 v[252:253], v[178:179], s[54:55] op_sel_hi:[1,0]
	v_pk_mul_f32 v[228:229], v[210:211], s[54:55] op_sel_hi:[1,0]
	v_pk_mul_f32 v[230:231], v[212:213], s[54:55] op_sel_hi:[1,0]
	v_exp_f32_e32 v218, v218
	v_exp_f32_e32 v219, v219
	v_exp_f32_e32 v252, v252
	v_exp_f32_e32 v253, v253
	v_exp_f32_e32 v228, v228
	v_exp_f32_e32 v229, v229
	v_exp_f32_e32 v230, v230
	v_exp_f32_e32 v231, v231
	v_pk_add_f32 v[218:219], v[218:219], s[56:57] op_sel_hi:[1,0]
	v_pk_add_f32 v[252:253], v[252:253], s[56:57] op_sel_hi:[1,0]
	v_pk_add_f32 v[228:229], v[228:229], s[56:57] op_sel_hi:[1,0]
	v_pk_add_f32 v[230:231], v[230:231], s[56:57] op_sel_hi:[1,0]
	v_rcp_f32_e32 v218, v218
	v_rcp_f32_e32 v219, v219
	v_rcp_f32_e32 v252, v252
	v_rcp_f32_e32 v253, v253
	v_rcp_f32_e32 v228, v228
	v_rcp_f32_e32 v229, v229
	v_rcp_f32_e32 v230, v230
	v_rcp_f32_e32 v231, v231
	v_pk_mul_f32 v[142:143], v[142:143], v[218:219]
	v_pk_mul_f32 v[178:179], v[178:179], v[252:253]
	v_pk_mul_f32 v[210:211], v[210:211], v[228:229]
	v_pk_mul_f32 v[212:213], v[212:213], v[230:231]
	v_pk_fma_f32 v[218:219], v[188:189], v[84:85], v[220:221]
	v_pk_fma_f32 v[252:253], v[188:189], v[28:29], v[220:221]
	v_pk_fma_f32 v[228:229], v[188:189], v[24:25], v[220:221]
	v_pk_fma_f32 v[230:231], v[188:189], v[72:73], v[220:221]
	v_pk_fma_f32 v[218:219], v[200:201], v[28:29], v[218:219]
	v_pk_fma_f32 v[252:253], v[180:181], v[84:85], v[252:253]
	v_pk_fma_f32 v[228:229], v[180:181], v[28:29], v[228:229]
	v_pk_fma_f32 v[230:231], v[180:181], v[24:25], v[230:231]
	v_pk_fma_f32 v[252:253], v[200:201], v[24:25], v[252:253]
	v_pk_fma_f32 v[228:229], v[200:201], v[72:73], v[228:229]
	v_fmac_f32_dpp v218, v72, v180 row_shr:1 row_mask:0xf bank_mask:0xf bound_ctrl:1
	v_fmac_f32_dpp v230, v84, v200 row_shl:1 row_mask:0xf bank_mask:0xf bound_ctrl:1
	v_fmac_f32_dpp v219, v73, v181 row_shr:1 row_mask:0xf bank_mask:0xf bound_ctrl:1
	v_fmac_f32_dpp v231, v85, v201 row_shl:1 row_mask:0xf bank_mask:0xf bound_ctrl:1
	v_pk_mul_f32 v[142:143], v[142:143], v[218:219]
	v_pk_mul_f32 v[178:179], v[178:179], v[252:253]
	v_pk_mul_f32 v[210:211], v[210:211], v[228:229]
	v_pk_mul_f32 v[212:213], v[212:213], v[230:231]
	v_cvt_pk_bf16_f32 v236, v142, v143
	v_cvt_pk_bf16_f32 v240, v178, v179
	v_cvt_pk_bf16_f32 v244, v210, v211
	v_cvt_pk_bf16_f32 v248, v212, v213
	v_pk_fma_f32 v[142:143], v[154:155], v[94:95], v[170:171]
	v_pk_fma_f32 v[178:179], v[154:155], v[38:39], v[170:171]
	v_pk_fma_f32 v[210:211], v[154:155], v[34:35], v[170:171]
	v_pk_fma_f32 v[212:213], v[154:155], v[78:79], v[170:171]
	v_pk_fma_f32 v[142:143], v[162:163], v[38:39], v[142:143]
	v_pk_fma_f32 v[178:179], v[146:147], v[94:95], v[178:179]
	v_pk_fma_f32 v[210:211], v[146:147], v[38:39], v[210:211]
	v_pk_fma_f32 v[212:213], v[146:147], v[34:35], v[212:213]
	v_pk_fma_f32 v[178:179], v[162:163], v[34:35], v[178:179]
	v_pk_fma_f32 v[210:211], v[162:163], v[78:79], v[210:211]
	v_fmac_f32_dpp v142, v78, v146 row_shr:1 row_mask:0xf bank_mask:0xf bound_ctrl:1
	v_fmac_f32_dpp v212, v94, v162 row_shl:1 row_mask:0xf bank_mask:0xf bound_ctrl:1
	v_fmac_f32_dpp v143, v79, v147 row_shr:1 row_mask:0xf bank_mask:0xf bound_ctrl:1
	v_fmac_f32_dpp v213, v95, v163 row_shl:1 row_mask:0xf bank_mask:0xf bound_ctrl:1
; __device__ __forceinline__ unsigned cvt_pk_bf16(float lo, float hi) { unsigned r; asm volatile("v_cvt_pk_bf16_f32 %0, %1, %2" : "=v"(r) : "v"(lo), "v"(hi)); return r; }
; template <int CTRL> __device__ __forceinline__ float dppz(float v) { return __int_as_float(__builtin_amdgcn_update_dpp(0, __float_as_int(v), CTRL, 0xf, 0xf, true)); }
;     __device__ __forceinline__ void operator()(f32x4 (&acc)[2][2][4][2], const Unit& u, int wr, int wc, int fr, int fq, const LAS float* rtab) const {
;     ...
;                 for (int m = 0; m < 4; ++m) {
;                     float y[4];
; #pragma unroll
;                     for (int jj = 0; jj < 4; ++jj) {
;                         const float gc = acc[ai][0][m][n][jj], uc = acc[ai][1][m][n][jj];
;                         const float gb = m > 0 ? acc[ai][0][m - 1][n][jj] : 0.f, ga = m < 3 ? acc[ai][0][m + 1][n][jj] : 0.f;
;                         const float ub = m > 0 ? acc[ai][1][m - 1][n][jj] : 0.f, ua = m < 3 ? acc[ai][1][m + 1][n][jj] : 0.f;
;                         const float gp = dppz<0x111>(gc) + dppz<0x10F>(gb), gn = dppz<0x101>(gc) + dppz<0x11F>(ga);
;                         const float up = dppz<0x111>(uc) + dppz<0x10F>(ub), un = dppz<0x101>(uc) + dppz<0x11F>(ua);
;                         const float hg = wg0[jj] * gp + wg1[jj] * gc + wg2[jj] * gn + bg[jj];
;                         const float hu = wu0[jj] * up + wu1[jj] * uc + wu2[jj] * un + bu[jj];
;                         const float sg = __builtin_amdgcn_rcpf(1.f + __builtin_amdgcn_exp2f(-1.4426950408889634f * hg));
;                         y[jj] = hg * sg * hu; }
;                     u32x2 pk; pk.x = cvt_pk_bf16(y[0], y[1]); pk.y = cvt_pk_bf16(y[2], y[3]);
;                     if (n == 0) ypk[ai][m] = pk;
;                     else {
;                         const bool deferred = (m == 0 && fr == 0) || (m == 3 && fr == 15);
;                         if (!deferred) { u32x4 w; w.x = ypk[ai][m].x; w.y = ypk[ai][m].y; w.z = pk.x; w.w = pk.y; *(u32x4*)(act + (size_t)(r64 + m * 16 + fr) * DFF + c0) = w; } }
	v_pk_mul_f32 v[218:219], v[142:143], s[54:55] op_sel_hi:[1,0]
	v_pk_mul_f32 v[252:253], v[178:179], s[54:55] op_sel_hi:[1,0]
	v_pk_mul_f32 v[228:229], v[210:211], s[54:55] op_sel_hi:[1,0]
	v_pk_mul_f32 v[230:231], v[212:213], s[54:55] op_sel_hi:[1,0]
	v_exp_f32_e32 v218, v218
	v_exp_f32_e32 v219, v219
	v_exp_f32_e32 v252, v252
	v_exp_f32_e32 v253, v253
	v_exp_f32_e32 v228, v228
	v_exp_f32_e32 v229, v229
	v_exp_f32_e32 v230, v230
	v_exp_f32_e32 v231, v231
	v_pk_add_f32 v[218:219], v[218:219], s[56:57] op_sel_hi:[1,0]
	v_pk_add_f32 v[252:253], v[252:253], s[56:57] op_sel_hi:[1,0]
	v_pk_add_f32 v[228:229], v[228:229], s[56:57] op_sel_hi:[1,0]
	v_pk_add_f32 v[230:231], v[230:231], s[56:57] op_sel_hi:[1,0]
	v_rcp_f32_e32 v218, v218
	v_rcp_f32_e32 v219, v219
	v_rcp_f32_e32 v252, v252
	v_rcp_f32_e32 v253, v253
	v_rcp_f32_e32 v228, v228
	v_rcp_f32_e32 v229, v229
	v_rcp_f32_e32 v230, v230
	v_rcp_f32_e32 v231, v231
	v_pk_mul_f32 v[142:143], v[142:143], v[218:219]
	v_pk_mul_f32 v[178:179], v[178:179], v[252:253]
	v_pk_mul_f32 v[210:211], v[210:211], v[228:229]
	v_pk_mul_f32 v[212:213], v[212:213], v[230:231]
	v_pk_fma_f32 v[218:219], v[190:191], v[86:87], v[222:223]
	v_pk_fma_f32 v[252:253], v[190:191], v[30:31], v[222:223]
	v_pk_fma_f32 v[228:229], v[190:191], v[26:27], v[222:223]
	v_pk_fma_f32 v[230:231], v[190:191], v[74:75], v[222:223]
	v_pk_fma_f32 v[218:219], v[202:203], v[30:31], v[218:219]
	v_pk_fma_f32 v[252:253], v[182:183], v[86:87], v[252:253]
	v_pk_fma_f32 v[228:229], v[182:183], v[30:31], v[228:229]
	v_pk_fma_f32 v[230:231], v[182:183], v[26:27], v[230:231]
	v_pk_fma_f32 v[252:253], v[202:203], v[26:27], v[252:253]
	v_pk_fma_f32 v[228:229], v[202:203], v[74:75], v[228:229]
	v_fmac_f32_dpp v218, v74, v182 row_shr:1 row_mask:0xf bank_mask:0xf bound_ctrl:1
	v_fmac_f32_dpp v230, v86, v202 row_shl:1 row_mask:0xf bank_mask:0xf bound_ctrl:1
	v_fmac_f32_dpp v219, v75, v183 row_shr:1 row_mask:0xf bank_mask:0xf bound_ctrl:1
	v_fmac_f32_dpp v231, v87, v203 row_shl:1 row_mask:0xf bank_mask:0xf bound_ctrl:1
	v_pk_mul_f32 v[142:143], v[142:143], v[218:219]
	v_pk_mul_f32 v[178:179], v[178:179], v[252:253]
	v_pk_mul_f32 v[210:211], v[210:211], v[228:229]
	v_pk_mul_f32 v[212:213], v[212:213], v[230:231]
	v_cvt_pk_bf16_f32 v237, v142, v143
	v_cvt_pk_bf16_f32 v241, v178, v179
	v_cvt_pk_bf16_f32 v245, v210, v211
	v_cvt_pk_bf16_f32 v249, v212, v213
	v_pk_fma_f32 v[142:143], v[156:157], v[88:89], v[172:173]
	v_pk_fma_f32 v[178:179], v[156:157], v[12:13], v[172:173]
	v_pk_fma_f32 v[210:211], v[156:157], v[4:5], v[172:173]
	v_pk_fma_f32 v[212:213], v[156:157], v[56:57], v[172:173]
	v_pk_fma_f32 v[142:143], v[164:165], v[12:13], v[142:143]
	v_pk_fma_f32 v[178:179], v[148:149], v[88:89], v[178:179]
	v_pk_fma_f32 v[210:211], v[148:149], v[12:13], v[210:211]
	v_pk_fma_f32 v[212:213], v[148:149], v[4:5], v[212:213]
	v_pk_fma_f32 v[178:179], v[164:165], v[4:5], v[178:179]
	v_pk_fma_f32 v[210:211], v[164:165], v[56:57], v[210:211]
	v_fmac_f32_dpp v142, v56, v148 row_shr:1 row_mask:0xf bank_mask:0xf bound_ctrl:1
	v_fmac_f32_dpp v212, v88, v164 row_shl:1 row_mask:0xf bank_mask:0xf bound_ctrl:1
	v_fmac_f32_dpp v143, v57, v149 row_shr:1 row_mask:0xf bank_mask:0xf bound_ctrl:1
	v_fmac_f32_dpp v213, v89, v165 row_shl:1 row_mask:0xf bank_mask:0xf bound_ctrl:1
	v_pk_mul_f32 v[218:219], v[142:143], s[54:55] op_sel_hi:[1,0]
	v_pk_mul_f32 v[252:253], v[178:179], s[54:55] op_sel_hi:[1,0]
	v_pk_mul_f32 v[228:229], v[210:211], s[54:55] op_sel_hi:[1,0]
	v_pk_mul_f32 v[230:231], v[212:213], s[54:55] op_sel_hi:[1,0]
	v_exp_f32_e32 v218, v218
	v_exp_f32_e32 v219, v219
	v_exp_f32_e32 v252, v252
	v_exp_f32_e32 v253, v253
	v_exp_f32_e32 v228, v228
	v_exp_f32_e32 v229, v229
	v_exp_f32_e32 v230, v230
	v_exp_f32_e32 v231, v231
	v_pk_add_f32 v[218:219], v[218:219], s[56:57] op_sel_hi:[1,0]
	v_pk_add_f32 v[252:253], v[252:253], s[56:57] op_sel_hi:[1,0]
	v_pk_add_f32 v[228:229], v[228:229], s[56:57] op_sel_hi:[1,0]
	v_pk_add_f32 v[230:231], v[230:231], s[56:57] op_sel_hi:[1,0]
	v_rcp_f32_e32 v218, v218
	v_rcp_f32_e32 v219, v219
	v_rcp_f32_e32 v252, v252
	v_rcp_f32_e32 v253, v253
	v_rcp_f32_e32 v228, v228
	v_rcp_f32_e32 v229, v229
	v_rcp_f32_e32 v230, v230
	v_rcp_f32_e32 v231, v231
	v_pk_mul_f32 v[142:143], v[142:143], v[218:219]
	v_pk_mul_f32 v[178:179], v[178:179], v[252:253]
	v_pk_mul_f32 v[210:211], v[210:211], v[228:229]
	v_pk_mul_f32 v[212:213], v[212:213], v[230:231]
	v_pk_fma_f32 v[218:219], v[196:197], v[80:81], v[224:225]
	v_pk_fma_f32 v[252:253], v[196:197], v[8:9], v[224:225]
	v_pk_fma_f32 v[228:229], v[196:197], v[0:1], v[224:225]
	v_pk_fma_f32 v[230:231], v[196:197], v[40:41], v[224:225]
	v_pk_fma_f32 v[218:219], v[204:205], v[8:9], v[218:219]
	v_pk_fma_f32 v[252:253], v[184:185], v[80:81], v[252:253]
;     __device__ __forceinline__ void operator()(f32x4 (&acc)[2][2][4][2], const Unit& u, int wr, int wc, int fr, int fq, const LAS float* rtab) const {
;     ...
;                 for (int m = 0; m < 4; ++m) {
;                     float y[4];
; #pragma unroll
;                     for (int jj = 0; jj < 4; ++jj) {
;                         const float gc = acc[ai][0][m][n][jj], uc = acc[ai][1][m][n][jj];
;                         const float gb = m > 0 ? acc[ai][0][m - 1][n][jj] : 0.f, ga = m < 3 ? acc[ai][0][m + 1][n][jj] : 0.f;
;                         const float ub = m > 0 ? acc[ai][1][m - 1][n][jj] : 0.f, ua = m < 3 ? acc[ai][1][m + 1][n][jj] : 0.f;
;                         const float gp = dppz<0x111>(gc) + dppz<0x10F>(gb), gn = dppz<0x101>(gc) + dppz<0x11F>(ga);
;                         const float up = dppz<0x111>(uc) + dppz<0x10F>(ub), un = dppz<0x101>(uc) + dppz<0x11F>(ua);
;                         const float hg = wg0[jj] * gp + wg1[jj] * gc + wg2[jj] * gn + bg[jj];
;                         const float hu = wu0[jj] * up + wu1[jj] * uc + wu2[jj] * un + bu[jj];
;                         const float sg = __builtin_amdgcn_rcpf(1.f + __builtin_amdgcn_exp2f(-1.4426950408889634f * hg));
;                         y[jj] = hg * sg * hu; }
;                     u32x2 pk; pk.x = cvt_pk_bf16(y[0], y[1]); pk.y = cvt_pk_bf16(y[2], y[3]);
;                     if (n == 0) ypk[ai][m] = pk;
;                     else {
;                         const bool deferred = (m == 0 && fr == 0) || (m == 3 && fr == 15);
;                         if (!deferred) { u32x4 w; w.x = ypk[ai][m].x; w.y = ypk[ai][m].y; w.z = pk.x; w.w = pk.y; *(u32x4*)(act + (size_t)(r64 + m * 16 + fr) * DFF + c0) = w; } }
; template <class Epi, bool KREV = false>
; __device__ __forceinline__ void gemm_phase(LAS unsigned char* lds, const Gemm g, const StaticOrder& S, const Epi& E, int wave_s) {
;     ...
;         if (!has_next) break;
; #pragma unroll
;         for (int a = 0; a < 2; ++a)
; #pragma unroll
;             for (int b = 0; b < 2; ++b)
; #pragma unroll
;                 for (int m = 0; m < 4; ++m)
; #pragma unroll
;                     for (int n = 0; n < 2; ++n) acc[a][b][m][n] = (f32x4){0.f, 0.f, 0.f, 0.f};
;         cur = nxt; cA = nA; cB = nB; ++ui;
	v_pk_fma_f32 v[228:229], v[184:185], v[8:9], v[228:229]
	v_pk_fma_f32 v[230:231], v[184:185], v[0:1], v[230:231]
	v_pk_fma_f32 v[252:253], v[204:205], v[0:1], v[252:253]
	v_pk_fma_f32 v[228:229], v[204:205], v[40:41], v[228:229]
	v_fmac_f32_dpp v218, v40, v184 row_shr:1 row_mask:0xf bank_mask:0xf bound_ctrl:1
	v_fmac_f32_dpp v230, v80, v204 row_shl:1 row_mask:0xf bank_mask:0xf bound_ctrl:1
	v_fmac_f32_dpp v219, v41, v185 row_shr:1 row_mask:0xf bank_mask:0xf bound_ctrl:1
	v_fmac_f32_dpp v231, v81, v205 row_shl:1 row_mask:0xf bank_mask:0xf bound_ctrl:1
	v_pk_mul_f32 v[142:143], v[142:143], v[218:219]
	v_pk_mul_f32 v[178:179], v[178:179], v[252:253]
	v_pk_mul_f32 v[210:211], v[210:211], v[228:229]
	v_pk_mul_f32 v[212:213], v[212:213], v[230:231]
	v_cvt_pk_bf16_f32 v238, v142, v143
	v_cvt_pk_bf16_f32 v242, v178, v179
	v_cvt_pk_bf16_f32 v246, v210, v211
	v_cvt_pk_bf16_f32 v250, v212, v213
	v_pk_fma_f32 v[142:143], v[158:159], v[90:91], v[174:175]
	v_pk_fma_f32 v[178:179], v[158:159], v[14:15], v[174:175]
	v_pk_fma_f32 v[210:211], v[158:159], v[6:7], v[174:175]
	v_pk_fma_f32 v[212:213], v[158:159], v[58:59], v[174:175]
	v_pk_fma_f32 v[142:143], v[166:167], v[14:15], v[142:143]
	v_pk_fma_f32 v[178:179], v[150:151], v[90:91], v[178:179]
	v_pk_fma_f32 v[210:211], v[150:151], v[14:15], v[210:211]
	v_pk_fma_f32 v[212:213], v[150:151], v[6:7], v[212:213]
	v_pk_fma_f32 v[178:179], v[166:167], v[6:7], v[178:179]
	v_pk_fma_f32 v[210:211], v[166:167], v[58:59], v[210:211]
	v_fmac_f32_dpp v142, v58, v150 row_shr:1 row_mask:0xf bank_mask:0xf bound_ctrl:1
	v_fmac_f32_dpp v212, v90, v166 row_shl:1 row_mask:0xf bank_mask:0xf bound_ctrl:1
	v_fmac_f32_dpp v143, v59, v151 row_shr:1 row_mask:0xf bank_mask:0xf bound_ctrl:1
	v_fmac_f32_dpp v213, v91, v167 row_shl:1 row_mask:0xf bank_mask:0xf bound_ctrl:1
	v_pk_mul_f32 v[218:219], v[142:143], s[54:55] op_sel_hi:[1,0]
	v_pk_mul_f32 v[252:253], v[178:179], s[54:55] op_sel_hi:[1,0]
	v_pk_mul_f32 v[228:229], v[210:211], s[54:55] op_sel_hi:[1,0]
	v_pk_mul_f32 v[230:231], v[212:213], s[54:55] op_sel_hi:[1,0]
	v_exp_f32_e32 v218, v218
	v_exp_f32_e32 v219, v219
	v_exp_f32_e32 v252, v252
	v_exp_f32_e32 v253, v253
	v_exp_f32_e32 v228, v228
	v_exp_f32_e32 v229, v229
	v_exp_f32_e32 v230, v230
	v_exp_f32_e32 v231, v231
	v_pk_add_f32 v[218:219], v[218:219], s[56:57] op_sel_hi:[1,0]
	v_pk_add_f32 v[252:253], v[252:253], s[56:57] op_sel_hi:[1,0]
	v_pk_add_f32 v[228:229], v[228:229], s[56:57] op_sel_hi:[1,0]
	v_pk_add_f32 v[230:231], v[230:231], s[56:57] op_sel_hi:[1,0]
	v_rcp_f32_e32 v218, v218
	v_rcp_f32_e32 v219, v219
	v_rcp_f32_e32 v252, v252
	v_rcp_f32_e32 v253, v253
	v_rcp_f32_e32 v228, v228
	v_rcp_f32_e32 v229, v229
	v_rcp_f32_e32 v230, v230
	v_rcp_f32_e32 v231, v231
	v_pk_mul_f32 v[142:143], v[142:143], v[218:219]
	v_pk_mul_f32 v[178:179], v[178:179], v[252:253]
	v_pk_mul_f32 v[210:211], v[210:211], v[228:229]
	v_pk_mul_f32 v[212:213], v[212:213], v[230:231]
	v_pk_fma_f32 v[218:219], v[198:199], v[82:83], v[226:227]
	v_pk_fma_f32 v[252:253], v[198:199], v[10:11], v[226:227]
	v_pk_fma_f32 v[228:229], v[198:199], v[2:3], v[226:227]
	v_pk_fma_f32 v[230:231], v[198:199], v[42:43], v[226:227]
	v_pk_fma_f32 v[218:219], v[206:207], v[10:11], v[218:219]
	v_pk_fma_f32 v[252:253], v[186:187], v[82:83], v[252:253]
	v_pk_fma_f32 v[228:229], v[186:187], v[10:11], v[228:229]
	v_pk_fma_f32 v[230:231], v[186:187], v[2:3], v[230:231]
	v_pk_fma_f32 v[252:253], v[206:207], v[2:3], v[252:253]
	v_pk_fma_f32 v[228:229], v[206:207], v[42:43], v[228:229]
	v_fmac_f32_dpp v218, v42, v186 row_shr:1 row_mask:0xf bank_mask:0xf bound_ctrl:1
	v_fmac_f32_dpp v230, v82, v206 row_shl:1 row_mask:0xf bank_mask:0xf bound_ctrl:1
	v_fmac_f32_dpp v219, v43, v187 row_shr:1 row_mask:0xf bank_mask:0xf bound_ctrl:1
	v_fmac_f32_dpp v231, v83, v207 row_shl:1 row_mask:0xf bank_mask:0xf bound_ctrl:1
	v_pk_mul_f32 v[142:143], v[142:143], v[218:219]
	v_pk_mul_f32 v[178:179], v[178:179], v[252:253]
	v_pk_mul_f32 v[210:211], v[210:211], v[228:229]
	v_pk_mul_f32 v[212:213], v[212:213], v[230:231]
	v_cvt_pk_bf16_f32 v239, v142, v143
	v_cvt_pk_bf16_f32 v243, v178, v179
	v_cvt_pk_bf16_f32 v247, v210, v211
	v_cvt_pk_bf16_f32 v251, v212, v213
	s_add_u32 s58, s28, 0x160000
	s_addc_u32 s59, s29, 0
	s_mov_b64 exec, s[12:13]
	global_store_dwordx4 v234, v[236:239], s[58:59]
	s_mov_b64 exec, -1
	s_add_u32 s58, s28, 0x162c00
	s_addc_u32 s59, s29, 0
	global_store_dwordx4 v234, v[240:243], s[58:59]
	s_add_u32 s58, s28, 0x165800
	s_addc_u32 s59, s29, 0
	global_store_dwordx4 v234, v[244:247], s[58:59]
	s_add_u32 s58, s28, 0x168400
	s_addc_u32 s59, s29, 0
	s_mov_b64 exec, s[10:11]
	global_store_dwordx4 v234, v[248:251], s[58:59]
	s_mov_b64 exec, -1
	s_andn2_b64 vcc, exec, s[52:53]
	s_mov_b64 s[52:53], -1
	s_cbranch_vccnz .LBB0_834
